# GEMM main loops: older co-resident wave raises priority for the MFMA groups and drops it for the staging section, younger wave stays raised (attention-style scheme)
# speedup vs baseline: 1.0051x; 1.0017x over previous
.LBB0_37:
	v_add_u32_e32 v186, v200, v202
	ds_read_b128 v[208:211], v186 offset:24576
	ds_read_b128 v[212:215], v186 offset:26624
	ds_read_b128 v[216:219], v186 offset:28672
	ds_read_b128 v[238:241], v186 offset:30720
	v_add_u32_e32 v205, v203, v202
	ds_read_b128 v[244:247], v205 offset:40960
	ds_read_b128 v[248:251], v205 offset:43008
	v_mfma_f32_32x32x16_bf16 v[112:127], v[140:143], v[148:151], v[112:127]
	v_add_u32_e32 v206, v200, v204
	v_add_u32_e32 v207, v203, v204
	v_mfma_f32_32x32x16_bf16 v[96:111], v[140:143], v[144:147], v[96:111]
	v_mfma_f32_32x32x16_bf16 v[80:95], v[136:139], v[148:151], v[80:95]
	v_mfma_f32_32x32x16_bf16 v[64:79], v[136:139], v[144:147], v[64:79]
	v_mfma_f32_32x32x16_bf16 v[48:63], v[132:135], v[148:151], v[48:63]
	v_mfma_f32_32x32x16_bf16 v[32:47], v[132:135], v[144:147], v[32:47]
	v_mfma_f32_32x32x16_bf16 v[16:31], v[128:131], v[148:151], v[16:31]
	v_mfma_f32_32x32x16_bf16 v[0:15], v[128:131], v[144:147], v[0:15]
	ds_read_b128 v[128:131], v206 offset:24576
	ds_read_b128 v[132:135], v206 offset:26624
	ds_read_b128 v[136:139], v206 offset:28672
	ds_read_b128 v[140:143], v206 offset:30720
	ds_read_b128 v[144:147], v207 offset:40960
	ds_read_b128 v[148:151], v207 offset:43008
	s_waitcnt lgkmcnt(7)
	v_mfma_f32_32x32x16_bf16 v[112:127], v[208:211], v[244:247], v[112:127]
	s_waitcnt lgkmcnt(6)
	v_mfma_f32_32x32x16_bf16 v[96:111], v[208:211], v[248:251], v[96:111]
	v_mfma_f32_32x32x16_bf16 v[80:95], v[212:215], v[244:247], v[80:95]
	v_mfma_f32_32x32x16_bf16 v[64:79], v[212:215], v[248:251], v[64:79]
	v_mfma_f32_32x32x16_bf16 v[48:63], v[216:219], v[244:247], v[48:63]
	v_mfma_f32_32x32x16_bf16 v[32:47], v[216:219], v[248:251], v[32:47]
	v_mfma_f32_32x32x16_bf16 v[16:31], v[238:241], v[244:247], v[16:31]
	v_mfma_f32_32x32x16_bf16 v[0:15], v[238:241], v[248:251], v[0:15]
	s_getreg_b32 s39, hwreg(HW_REG_HW_ID, 0, 4)
	s_bitcmp1_b32 s39, 0
	s_cbranch_scc1 .Lgp0
	s_setprio 0
.Lgp0:
	s_waitcnt vmcnt(2)
	ds_write_b128 v201, v[164:167] offset:12288
	v_lshl_add_u64 v[164:165], v[198:199], 0, s[8:9]
	ds_write_b128 v201, v[152:155]
	v_add_co_u32_e32 v152, vcc, s92, v164
	ds_write_b128 v201, v[156:159] offset:4096
	s_nop 0
	v_addc_co_u32_e32 v153, vcc, 0, v165, vcc
	v_add_co_u32_e32 v156, vcc, s93, v164
	ds_write_b128 v201, v[160:163] offset:8192
	s_nop 0
	v_addc_co_u32_e32 v157, vcc, 0, v165, vcc
	v_add_co_u32_e32 v160, vcc, s88, v164
	s_waitcnt vmcnt(0)
	ds_write_b128 v201, v[172:175] offset:20480
	v_addc_co_u32_e32 v161, vcc, 0, v165, vcc
	v_add_co_u32_e32 v164, vcc, s89, v164
	v_lshl_add_u64 v[172:173], v[196:197], 0, s[8:9]
	s_nop 0
	v_addc_co_u32_e32 v165, vcc, 0, v165, vcc
	s_mov_b32 s16, 0x3500000
	ds_write_b128 v201, v[168:171] offset:16384
	v_add_co_u32_e32 v168, vcc, s16, v172
	s_mov_b32 s16, 0x3540000
	s_nop 0
	v_addc_co_u32_e32 v169, vcc, 0, v173, vcc
	v_add_co_u32_e32 v172, vcc, s16, v172
	global_load_dwordx4 v[152:155], v[152:153], off offset:192
	s_nop 0
	v_addc_co_u32_e32 v173, vcc, 0, v173, vcc
	global_load_dwordx4 v[156:159], v[156:157], off offset:192
	s_nop 0
	global_load_dwordx4 v[160:163], v[160:161], off offset:192
	s_nop 0
	global_load_dwordx4 v[164:167], v[164:165], off offset:192
	s_nop 0
	global_load_dwordx4 v[168:171], v[168:169], off offset:192
	s_nop 0
	global_load_dwordx4 v[172:175], v[172:173], off offset:192
	s_waitcnt lgkmcnt(0)
	s_barrier
	s_setprio 1
	ds_read_b128 v[208:211], v186
	ds_read_b128 v[212:215], v186 offset:2048
	ds_read_b128 v[216:219], v186 offset:4096
	ds_read_b128 v[238:241], v186 offset:6144
	ds_read_b128 v[244:247], v205 offset:16384
	ds_read_b128 v[248:251], v205 offset:18432
	v_mfma_f32_32x32x16_bf16 v[112:127], v[128:131], v[144:147], v[112:127]
	v_mfma_f32_32x32x16_bf16 v[96:111], v[128:131], v[148:151], v[96:111]
	v_mfma_f32_32x32x16_bf16 v[80:95], v[132:135], v[144:147], v[80:95]
	v_mfma_f32_32x32x16_bf16 v[64:79], v[132:135], v[148:151], v[64:79]
	v_mfma_f32_32x32x16_bf16 v[48:63], v[136:139], v[144:147], v[48:63]
	v_mfma_f32_32x32x16_bf16 v[32:47], v[136:139], v[148:151], v[32:47]
	v_mfma_f32_32x32x16_bf16 v[16:31], v[140:143], v[144:147], v[16:31]
	v_mfma_f32_32x32x16_bf16 v[0:15], v[140:143], v[148:151], v[0:15]
	ds_read_b128 v[140:143], v206
	ds_read_b128 v[136:139], v206 offset:2048
	ds_read_b128 v[132:135], v206 offset:4096
	ds_read_b128 v[128:131], v206 offset:6144
	ds_read_b128 v[148:151], v207 offset:16384
	ds_read_b128 v[144:147], v207 offset:18432
	s_waitcnt lgkmcnt(7)
	v_mfma_f32_32x32x16_bf16 v[112:127], v[208:211], v[244:247], v[112:127]
	s_waitcnt lgkmcnt(6)
	v_mfma_f32_32x32x16_bf16 v[96:111], v[208:211], v[248:251], v[96:111]
	v_mfma_f32_32x32x16_bf16 v[80:95], v[212:215], v[244:247], v[80:95]
	v_mfma_f32_32x32x16_bf16 v[64:79], v[212:215], v[248:251], v[64:79]
	v_mfma_f32_32x32x16_bf16 v[48:63], v[216:219], v[244:247], v[48:63]
	v_mfma_f32_32x32x16_bf16 v[32:47], v[216:219], v[248:251], v[32:47]
	v_mfma_f32_32x32x16_bf16 v[16:31], v[238:241], v[244:247], v[16:31]
	v_mfma_f32_32x32x16_bf16 v[0:15], v[238:241], v[248:251], v[0:15]
	s_getreg_b32 s39, hwreg(HW_REG_HW_ID, 0, 4)
	s_bitcmp1_b32 s39, 0
	s_cbranch_scc1 .Lgp1
	s_setprio 0
.Lgp1:
	s_min_u32 s16, s15, 60
	s_lshl_b32 s66, s16, 6
	s_add_i32 s16, s66, 0xc0
	s_mov_b32 s17, s67
	s_waitcnt vmcnt(5)
	ds_write_b128 v201, v[152:155] offset:24576
	s_waitcnt vmcnt(4)
	ds_write_b128 v201, v[156:159] offset:28672
	s_waitcnt vmcnt(3)
	ds_write_b128 v201, v[160:163] offset:32768
	s_waitcnt vmcnt(2)
	ds_write_b128 v201, v[164:167] offset:36864
	s_waitcnt vmcnt(1)
	ds_write_b128 v201, v[168:171] offset:40960
	s_waitcnt vmcnt(0)
	ds_write_b128 v201, v[172:175] offset:45056
	v_lshl_add_u64 v[152:153], v[176:177], 0, s[66:67]
	v_lshl_add_u64 v[156:157], v[180:181], 0, s[16:17]
	v_lshl_add_u64 v[160:161], v[182:183], 0, s[16:17]
	v_lshl_add_u64 v[164:165], v[192:193], 0, s[16:17]
	v_lshl_add_u64 v[168:169], v[178:179], 0, s[66:67]
	v_lshl_add_u64 v[172:173], v[194:195], 0, s[16:17]
	global_load_dwordx4 v[152:155], v[152:153], off offset:192
	s_add_i32 s15, s15, 2
	global_load_dwordx4 v[156:159], v[156:157], off
	s_add_u32 s8, s8, 0x80
	global_load_dwordx4 v[160:163], v[160:161], off
	s_addc_u32 s9, s9, 0
	global_load_dwordx4 v[164:167], v[164:165], off
	s_cmpk_lg_i32 s8, 0xf80
	global_load_dwordx4 v[168:171], v[168:169], off offset:192
	s_nop 0
	global_load_dwordx4 v[172:175], v[172:173], off
	s_waitcnt lgkmcnt(0)
	s_barrier
	s_setprio 1
	s_cbranch_scc1 .LBB0_37
	s_waitcnt vmcnt(5)
	ds_read_b128 v[152:155], v186 offset:24576
	s_waitcnt vmcnt(4)
	ds_read_b128 v[156:159], v186 offset:26624
	s_waitcnt vmcnt(3)
	ds_read_b128 v[160:163], v186 offset:28672
	s_waitcnt vmcnt(2)
	ds_read_b128 v[164:167], v186 offset:30720
	s_waitcnt vmcnt(1)
	ds_read_b128 v[168:171], v205 offset:40960
	s_waitcnt vmcnt(0)
	ds_read_b128 v[172:175], v205 offset:43008
	v_mfma_f32_32x32x16_bf16 v[112:127], v[140:143], v[148:151], v[112:127]
	v_mfma_f32_32x32x16_bf16 v[96:111], v[140:143], v[144:147], v[96:111]
	v_mfma_f32_32x32x16_bf16 v[80:95], v[136:139], v[148:151], v[80:95]
	v_mfma_f32_32x32x16_bf16 v[64:79], v[136:139], v[144:147], v[64:79]
	v_mfma_f32_32x32x16_bf16 v[48:63], v[132:135], v[148:151], v[48:63]
	v_mfma_f32_32x32x16_bf16 v[32:47], v[132:135], v[144:147], v[32:47]
	v_mfma_f32_32x32x16_bf16 v[16:31], v[128:131], v[148:151], v[16:31]
	v_mfma_f32_32x32x16_bf16 v[0:15], v[128:131], v[144:147], v[0:15]
	ds_read_b128 v[128:131], v206 offset:24576
	ds_read_b128 v[132:135], v206 offset:26624
	ds_read_b128 v[136:139], v206 offset:28672
	ds_read_b128 v[140:143], v206 offset:30720
	ds_read_b128 v[144:147], v207 offset:40960
	ds_read_b128 v[148:151], v207 offset:43008
	s_waitcnt lgkmcnt(7)
	v_mfma_f32_32x32x16_bf16 v[112:127], v[152:155], v[168:171], v[112:127]
	s_waitcnt lgkmcnt(6)
	v_mfma_f32_32x32x16_bf16 v[96:111], v[152:155], v[172:175], v[96:111]
	v_mfma_f32_32x32x16_bf16 v[80:95], v[156:159], v[168:171], v[80:95]
	v_mfma_f32_32x32x16_bf16 v[64:79], v[156:159], v[172:175], v[64:79]
	v_mfma_f32_32x32x16_bf16 v[48:63], v[160:163], v[168:171], v[48:63]
	v_mfma_f32_32x32x16_bf16 v[32:47], v[160:163], v[172:175], v[32:47]
	v_mfma_f32_32x32x16_bf16 v[16:31], v[164:167], v[168:171], v[16:31]
	v_mfma_f32_32x32x16_bf16 v[0:15], v[164:167], v[172:175], v[0:15]
	s_waitcnt lgkmcnt(1)
	v_mfma_f32_32x32x16_bf16 v[112:127], v[128:131], v[144:147], v[112:127]
	s_waitcnt lgkmcnt(0)
	s_barrier
	s_add_i32 s12, s12, s64
	s_add_i32 s11, s11, s55
	s_add_i32 s10, s10, s51
	s_cmpk_gt_i32 s12, 0x1ff
	v_mfma_f32_32x32x16_bf16 v[96:111], v[128:131], v[148:151], v[96:111]
	v_mov_b32_e32 v128, v189
	v_mov_b32_e32 v129, v189
	s_nop 2
	v_cvt_pk_bf16_f32 v112, v112, s0
	v_and_b32_e32 v130, 64, v129
	v_and_b32_e32 v129, 0xffffff80, v129
	v_and_b32_e32 v131, 31, v128
	v_lshrrev_b32_e32 v128, 3, v128
	v_add_u32_e32 v129, s14, v129
	v_and_or_b32 v128, v128, 4, v129
	v_or3_b32 v130, v131, v130, s13
	v_ashrrev_i32_e32 v131, 31, v130
	v_ashrrev_i32_e32 v129, 31, v128
	v_mfma_f32_32x32x16_bf16 v[80:95], v[132:135], v[144:147], v[80:95]
	v_lshl_add_u64 v[130:131], v[130:131], 1, s[6:7]
	v_cvt_pk_bf16_f32 v114, v114, s0
	v_cvt_pk_bf16_f32 v116, v116, s0
	v_cvt_pk_bf16_f32 v118, v118, s0
	v_cvt_pk_bf16_f32 v96, v96, s0
	v_cvt_pk_bf16_f32 v120, v120, s0
	v_cvt_pk_bf16_f32 v122, v122, s0
	v_mfma_f32_32x32x16_bf16 v[64:79], v[132:135], v[148:151], v[64:79]
	v_lshlrev_b64 v[132:133], 12, v[128:129]
	v_lshl_add_u64 v[132:133], v[130:131], 0, v[132:133]
	v_or_b32_e32 v134, 2, v128
	global_store_short v[132:133], v112, off
	v_or_b32_e32 v112, 1, v128
	v_ashrrev_i32_e32 v135, 31, v134
	v_cvt_pk_bf16_f32 v129, v113, s0
	v_ashrrev_i32_e32 v113, 31, v112
	v_lshlrev_b64 v[134:135], 12, v[134:135]
	v_mfma_f32_32x32x16_bf16 v[48:63], v[136:139], v[144:147], v[48:63]
	v_lshlrev_b64 v[112:113], 12, v[112:113]
	v_lshl_add_u64 v[134:135], v[130:131], 0, v[134:135]
	v_lshl_add_u64 v[112:113], v[130:131], 0, v[112:113]
	global_store_short v[134:135], v114, off
	v_or_b32_e32 v114, 3, v128
	global_store_short v[112:113], v129, off
	v_cvt_pk_bf16_f32 v129, v115, s0
	v_mfma_f32_32x32x16_bf16 v[32:47], v[136:139], v[148:151], v[32:47]
	v_or_b32_e32 v136, 8, v128
	v_ashrrev_i32_e32 v137, 31, v136
	v_ashrrev_i32_e32 v115, 31, v114
	v_lshlrev_b64 v[136:137], 12, v[136:137]
	v_lshlrev_b64 v[114:115], 12, v[114:115]
	v_lshl_add_u64 v[136:137], v[130:131], 0, v[136:137]
	v_or_b32_e32 v138, 10, v128
	v_lshl_add_u64 v[114:115], v[130:131], 0, v[114:115]
	global_store_short v[136:137], v116, off
	v_or_b32_e32 v116, 9, v128
	v_ashrrev_i32_e32 v139, 31, v138
	global_store_short v[114:115], v129, off
	v_cvt_pk_bf16_f32 v129, v117, s0
	v_ashrrev_i32_e32 v117, 31, v116
	v_lshlrev_b64 v[138:139], 12, v[138:139]
	v_mfma_f32_32x32x16_bf16 v[16:31], v[140:143], v[144:147], v[16:31]
	v_lshlrev_b64 v[116:117], 12, v[116:117]
	v_lshl_add_u64 v[138:139], v[130:131], 0, v[138:139]
	v_lshl_add_u64 v[116:117], v[130:131], 0, v[116:117]
	global_store_short v[138:139], v118, off
	v_or_b32_e32 v118, 11, v128
	global_store_short v[116:117], v129, off
	v_cvt_pk_bf16_f32 v129, v119, s0
	v_mfma_f32_32x32x16_bf16 v[0:15], v[140:143], v[148:151], v[0:15]
	v_or_b32_e32 v140, 16, v128
	v_ashrrev_i32_e32 v141, 31, v140
	v_ashrrev_i32_e32 v119, 31, v118
	v_lshlrev_b64 v[140:141], 12, v[140:141]
	global_store_short v[132:133], v96, off offset:64
	v_cvt_pk_bf16_f32 v96, v97, s0
	v_lshlrev_b64 v[118:119], 12, v[118:119]
	v_lshl_add_u64 v[140:141], v[130:131], 0, v[140:141]
	v_or_b32_e32 v142, 18, v128
	global_store_short v[112:113], v96, off offset:64
	v_cvt_pk_bf16_f32 v96, v98, s0
	v_lshl_add_u64 v[118:119], v[130:131], 0, v[118:119]
	global_store_short v[140:141], v120, off
	v_or_b32_e32 v120, 17, v128
	v_ashrrev_i32_e32 v143, 31, v142
	global_store_short v[134:135], v96, off offset:64
	v_cvt_pk_bf16_f32 v96, v99, s0
	global_store_short v[118:119], v129, off
	v_cvt_pk_bf16_f32 v129, v121, s0
	v_ashrrev_i32_e32 v121, 31, v120
	v_lshlrev_b64 v[142:143], 12, v[142:143]
	global_store_short v[114:115], v96, off offset:64
	v_cvt_pk_bf16_f32 v96, v100, s0
	v_lshlrev_b64 v[120:121], 12, v[120:121]
	v_lshl_add_u64 v[142:143], v[130:131], 0, v[142:143]
	v_or_b32_e32 v144, 24, v128
	global_store_short v[136:137], v96, off offset:64
	v_cvt_pk_bf16_f32 v96, v101, s0
	v_lshl_add_u64 v[120:121], v[130:131], 0, v[120:121]
	global_store_short v[142:143], v122, off
	v_or_b32_e32 v122, 19, v128
	v_ashrrev_i32_e32 v145, 31, v144
	global_store_short v[116:117], v96, off offset:64
	v_cvt_pk_bf16_f32 v96, v102, s0
	global_store_short v[120:121], v129, off
	v_cvt_pk_bf16_f32 v129, v123, s0
	v_ashrrev_i32_e32 v123, 31, v122
	v_lshlrev_b64 v[144:145], 12, v[144:145]
	global_store_short v[138:139], v96, off offset:64
	v_cvt_pk_bf16_f32 v96, v103, s0
	v_lshlrev_b64 v[122:123], 12, v[122:123]
	v_cvt_pk_bf16_f32 v124, v124, s0
	v_lshl_add_u64 v[144:145], v[130:131], 0, v[144:145]
	v_or_b32_e32 v146, 26, v128
	global_store_short v[118:119], v96, off offset:64
	v_cvt_pk_bf16_f32 v96, v104, s0
	v_lshl_add_u64 v[122:123], v[130:131], 0, v[122:123]
	global_store_short v[144:145], v124, off
	v_or_b32_e32 v124, 25, v128
	v_ashrrev_i32_e32 v147, 31, v146
	global_store_short v[140:141], v96, off offset:64
	v_cvt_pk_bf16_f32 v96, v105, s0
	global_store_short v[122:123], v129, off
	v_cvt_pk_bf16_f32 v129, v125, s0
	v_ashrrev_i32_e32 v125, 31, v124
	v_lshlrev_b64 v[146:147], 12, v[146:147]
	global_store_short v[120:121], v96, off offset:64
	v_cvt_pk_bf16_f32 v96, v106, s0
	v_lshlrev_b64 v[124:125], 12, v[124:125]
	v_cvt_pk_bf16_f32 v126, v126, s0
	v_lshl_add_u64 v[146:147], v[130:131], 0, v[146:147]
	global_store_short v[142:143], v96, off offset:64
	v_cvt_pk_bf16_f32 v96, v107, s0
	v_lshl_add_u64 v[124:125], v[130:131], 0, v[124:125]
	global_store_short v[146:147], v126, off
	v_or_b32_e32 v126, 27, v128
	global_store_short v[122:123], v96, off offset:64
	v_cvt_pk_bf16_f32 v96, v108, s0
	global_store_short v[124:125], v129, off
	v_cvt_pk_bf16_f32 v129, v127, s0
	v_ashrrev_i32_e32 v127, 31, v126
	global_store_short v[144:145], v96, off offset:64
	v_cvt_pk_bf16_f32 v96, v109, s0
	v_lshlrev_b64 v[126:127], 12, v[126:127]
	global_store_short v[124:125], v96, off offset:64
	v_cvt_pk_bf16_f32 v96, v110, s0
	v_lshl_add_u64 v[126:127], v[130:131], 0, v[126:127]
	global_store_short v[146:147], v96, off offset:64
	v_cvt_pk_bf16_f32 v96, v111, s0
	global_store_short v[126:127], v96, off offset:64
	v_or_b32_e32 v96, 32, v128
	v_ashrrev_i32_e32 v97, 31, v96
	v_lshlrev_b64 v[96:97], 12, v[96:97]
	v_cvt_pk_bf16_f32 v80, v80, s0
	v_lshl_add_u64 v[96:97], v[130:131], 0, v[96:97]
	global_store_short v[96:97], v80, off
	v_or_b32_e32 v80, 33, v128
	v_cvt_pk_bf16_f32 v98, v81, s0
	v_ashrrev_i32_e32 v81, 31, v80
	v_lshlrev_b64 v[80:81], 12, v[80:81]
	v_lshl_add_u64 v[80:81], v[130:131], 0, v[80:81]
	global_store_short v[80:81], v98, off
	v_or_b32_e32 v98, 34, v128
	v_ashrrev_i32_e32 v99, 31, v98
	v_lshlrev_b64 v[98:99], 12, v[98:99]
	v_cvt_pk_bf16_f32 v82, v82, s0
	v_lshl_add_u64 v[98:99], v[130:131], 0, v[98:99]
	global_store_short v[98:99], v82, off
	v_or_b32_e32 v82, 35, v128
	v_cvt_pk_bf16_f32 v100, v83, s0
	v_ashrrev_i32_e32 v83, 31, v82
	v_lshlrev_b64 v[82:83], 12, v[82:83]
	v_lshl_add_u64 v[82:83], v[130:131], 0, v[82:83]
	global_store_short v[82:83], v100, off
	v_or_b32_e32 v100, 40, v128
	v_ashrrev_i32_e32 v101, 31, v100
	v_lshlrev_b64 v[100:101], 12, v[100:101]
	v_cvt_pk_bf16_f32 v84, v84, s0
	v_lshl_add_u64 v[100:101], v[130:131], 0, v[100:101]
	global_store_short v[100:101], v84, off
	v_or_b32_e32 v84, 41, v128
	v_cvt_pk_bf16_f32 v102, v85, s0
	v_ashrrev_i32_e32 v85, 31, v84
	v_lshlrev_b64 v[84:85], 12, v[84:85]
	v_lshl_add_u64 v[84:85], v[130:131], 0, v[84:85]
	global_store_short v[84:85], v102, off
	v_or_b32_e32 v102, 42, v128
	v_ashrrev_i32_e32 v103, 31, v102
	v_lshlrev_b64 v[102:103], 12, v[102:103]
	v_cvt_pk_bf16_f32 v86, v86, s0
	v_lshl_add_u64 v[102:103], v[130:131], 0, v[102:103]
	global_store_short v[102:103], v86, off
	v_or_b32_e32 v86, 43, v128
	v_cvt_pk_bf16_f32 v104, v87, s0
	v_ashrrev_i32_e32 v87, 31, v86
	v_lshlrev_b64 v[86:87], 12, v[86:87]
	v_lshl_add_u64 v[86:87], v[130:131], 0, v[86:87]
	global_store_short v[86:87], v104, off
	v_or_b32_e32 v104, 48, v128
	v_ashrrev_i32_e32 v105, 31, v104
	v_lshlrev_b64 v[104:105], 12, v[104:105]
	v_cvt_pk_bf16_f32 v88, v88, s0
	v_lshl_add_u64 v[104:105], v[130:131], 0, v[104:105]
	global_store_short v[104:105], v88, off
	v_or_b32_e32 v88, 49, v128
	v_cvt_pk_bf16_f32 v106, v89, s0
	v_ashrrev_i32_e32 v89, 31, v88
	v_lshlrev_b64 v[88:89], 12, v[88:89]
	v_lshl_add_u64 v[88:89], v[130:131], 0, v[88:89]
	global_store_short v[88:89], v106, off
	v_or_b32_e32 v106, 50, v128
	v_ashrrev_i32_e32 v107, 31, v106
	v_lshlrev_b64 v[106:107], 12, v[106:107]
	v_cvt_pk_bf16_f32 v90, v90, s0
	v_lshl_add_u64 v[106:107], v[130:131], 0, v[106:107]
	global_store_short v[106:107], v90, off
	v_or_b32_e32 v90, 51, v128
	v_cvt_pk_bf16_f32 v108, v91, s0
	v_ashrrev_i32_e32 v91, 31, v90
	v_lshlrev_b64 v[90:91], 12, v[90:91]
	v_lshl_add_u64 v[90:91], v[130:131], 0, v[90:91]
	global_store_short v[90:91], v108, off
	v_or_b32_e32 v108, 56, v128
	v_cvt_pk_bf16_f32 v64, v64, s0
	v_ashrrev_i32_e32 v109, 31, v108
	global_store_short v[96:97], v64, off offset:64
	v_cvt_pk_bf16_f32 v64, v65, s0
	v_lshlrev_b64 v[108:109], 12, v[108:109]
	global_store_short v[80:81], v64, off offset:64
	v_cvt_pk_bf16_f32 v64, v66, s0
	v_cvt_pk_bf16_f32 v92, v92, s0
	v_lshl_add_u64 v[108:109], v[130:131], 0, v[108:109]
	global_store_short v[98:99], v64, off offset:64
	v_cvt_pk_bf16_f32 v64, v67, s0
	global_store_short v[108:109], v92, off
	v_or_b32_e32 v92, 57, v128
	global_store_short v[82:83], v64, off offset:64
	v_cvt_pk_bf16_f32 v64, v68, s0
	v_cvt_pk_bf16_f32 v110, v93, s0
	v_ashrrev_i32_e32 v93, 31, v92
	global_store_short v[100:101], v64, off offset:64
	v_cvt_pk_bf16_f32 v64, v69, s0
	v_lshlrev_b64 v[92:93], 12, v[92:93]
	global_store_short v[84:85], v64, off offset:64
	v_cvt_pk_bf16_f32 v64, v70, s0
	v_lshl_add_u64 v[92:93], v[130:131], 0, v[92:93]
	global_store_short v[102:103], v64, off offset:64
	v_cvt_pk_bf16_f32 v64, v71, s0
	global_store_short v[92:93], v110, off
	v_or_b32_e32 v110, 58, v128
	global_store_short v[86:87], v64, off offset:64
	v_cvt_pk_bf16_f32 v64, v72, s0
	v_ashrrev_i32_e32 v111, 31, v110
	global_store_short v[104:105], v64, off offset:64
	v_cvt_pk_bf16_f32 v64, v73, s0
	v_lshlrev_b64 v[110:111], 12, v[110:111]
	global_store_short v[88:89], v64, off offset:64
	v_cvt_pk_bf16_f32 v64, v74, s0
	v_cvt_pk_bf16_f32 v94, v94, s0
	v_lshl_add_u64 v[110:111], v[130:131], 0, v[110:111]
	global_store_short v[106:107], v64, off offset:64
	v_cvt_pk_bf16_f32 v64, v75, s0
	global_store_short v[110:111], v94, off
	v_or_b32_e32 v94, 59, v128
	global_store_short v[90:91], v64, off offset:64
	v_cvt_pk_bf16_f32 v64, v76, s0
	v_cvt_pk_bf16_f32 v112, v95, s0
	v_ashrrev_i32_e32 v95, 31, v94
	global_store_short v[108:109], v64, off offset:64
	v_cvt_pk_bf16_f32 v64, v77, s0
	v_lshlrev_b64 v[94:95], 12, v[94:95]
	global_store_short v[92:93], v64, off offset:64
	v_cvt_pk_bf16_f32 v64, v78, s0
	v_lshl_add_u64 v[94:95], v[130:131], 0, v[94:95]
	global_store_short v[110:111], v64, off offset:64
	v_cvt_pk_bf16_f32 v64, v79, s0
	global_store_short v[94:95], v64, off offset:64
	v_or_b32_e32 v64, 64, v128
	v_ashrrev_i32_e32 v65, 31, v64
	v_lshlrev_b64 v[64:65], 12, v[64:65]
	v_cvt_pk_bf16_f32 v48, v48, s0
	v_lshl_add_u64 v[64:65], v[130:131], 0, v[64:65]
	global_store_short v[64:65], v48, off
	v_or_b32_e32 v48, 0x41, v128
	v_cvt_pk_bf16_f32 v66, v49, s0
	v_ashrrev_i32_e32 v49, 31, v48
	v_lshlrev_b64 v[48:49], 12, v[48:49]
	v_lshl_add_u64 v[48:49], v[130:131], 0, v[48:49]
	global_store_short v[48:49], v66, off
	v_or_b32_e32 v66, 0x42, v128
	v_ashrrev_i32_e32 v67, 31, v66
	v_lshlrev_b64 v[66:67], 12, v[66:67]
	v_cvt_pk_bf16_f32 v50, v50, s0
	v_lshl_add_u64 v[66:67], v[130:131], 0, v[66:67]
	global_store_short v[66:67], v50, off
	v_or_b32_e32 v50, 0x43, v128
	v_cvt_pk_bf16_f32 v68, v51, s0
	v_ashrrev_i32_e32 v51, 31, v50
	v_lshlrev_b64 v[50:51], 12, v[50:51]
	v_lshl_add_u64 v[50:51], v[130:131], 0, v[50:51]
	global_store_short v[50:51], v68, off
	v_or_b32_e32 v68, 0x48, v128
	v_ashrrev_i32_e32 v69, 31, v68
	v_lshlrev_b64 v[68:69], 12, v[68:69]
	v_cvt_pk_bf16_f32 v52, v52, s0
	v_lshl_add_u64 v[68:69], v[130:131], 0, v[68:69]
	global_store_short v[68:69], v52, off
	v_or_b32_e32 v52, 0x49, v128
	v_cvt_pk_bf16_f32 v70, v53, s0
	v_ashrrev_i32_e32 v53, 31, v52
	v_lshlrev_b64 v[52:53], 12, v[52:53]
	v_lshl_add_u64 v[52:53], v[130:131], 0, v[52:53]
	global_store_short v[52:53], v70, off
	v_or_b32_e32 v70, 0x4a, v128
	v_ashrrev_i32_e32 v71, 31, v70
	v_lshlrev_b64 v[70:71], 12, v[70:71]
	v_cvt_pk_bf16_f32 v54, v54, s0
	v_lshl_add_u64 v[70:71], v[130:131], 0, v[70:71]
	global_store_short v[70:71], v54, off
	v_or_b32_e32 v54, 0x4b, v128
	v_cvt_pk_bf16_f32 v72, v55, s0
	v_ashrrev_i32_e32 v55, 31, v54
	v_lshlrev_b64 v[54:55], 12, v[54:55]
	v_lshl_add_u64 v[54:55], v[130:131], 0, v[54:55]
	global_store_short v[54:55], v72, off
	v_or_b32_e32 v72, 0x50, v128
	v_ashrrev_i32_e32 v73, 31, v72
	v_lshlrev_b64 v[72:73], 12, v[72:73]
	v_cvt_pk_bf16_f32 v56, v56, s0
	v_lshl_add_u64 v[72:73], v[130:131], 0, v[72:73]
	global_store_short v[72:73], v56, off
	v_or_b32_e32 v56, 0x51, v128
	v_cvt_pk_bf16_f32 v74, v57, s0
	v_ashrrev_i32_e32 v57, 31, v56
	v_lshlrev_b64 v[56:57], 12, v[56:57]
	v_lshl_add_u64 v[56:57], v[130:131], 0, v[56:57]
	global_store_short v[56:57], v74, off
	v_or_b32_e32 v74, 0x52, v128
	v_ashrrev_i32_e32 v75, 31, v74
	v_lshlrev_b64 v[74:75], 12, v[74:75]
	v_cvt_pk_bf16_f32 v58, v58, s0
	v_lshl_add_u64 v[74:75], v[130:131], 0, v[74:75]
	global_store_short v[74:75], v58, off
	v_or_b32_e32 v58, 0x53, v128
	v_cvt_pk_bf16_f32 v76, v59, s0
	v_ashrrev_i32_e32 v59, 31, v58
	v_lshlrev_b64 v[58:59], 12, v[58:59]
	v_lshl_add_u64 v[58:59], v[130:131], 0, v[58:59]
	global_store_short v[58:59], v76, off
	v_or_b32_e32 v76, 0x58, v128
	v_cvt_pk_bf16_f32 v32, v32, s0
	v_ashrrev_i32_e32 v77, 31, v76
	global_store_short v[64:65], v32, off offset:64
	v_cvt_pk_bf16_f32 v32, v33, s0
	v_lshlrev_b64 v[76:77], 12, v[76:77]
	global_store_short v[48:49], v32, off offset:64
	v_cvt_pk_bf16_f32 v32, v34, s0
	v_cvt_pk_bf16_f32 v60, v60, s0
	v_lshl_add_u64 v[76:77], v[130:131], 0, v[76:77]
	global_store_short v[66:67], v32, off offset:64
	v_cvt_pk_bf16_f32 v32, v35, s0
	global_store_short v[76:77], v60, off
	v_or_b32_e32 v60, 0x59, v128
	global_store_short v[50:51], v32, off offset:64
	v_cvt_pk_bf16_f32 v32, v36, s0
	v_cvt_pk_bf16_f32 v78, v61, s0
	v_ashrrev_i32_e32 v61, 31, v60
	global_store_short v[68:69], v32, off offset:64
	v_cvt_pk_bf16_f32 v32, v37, s0
	v_lshlrev_b64 v[60:61], 12, v[60:61]
	global_store_short v[52:53], v32, off offset:64
	v_cvt_pk_bf16_f32 v32, v38, s0
	v_lshl_add_u64 v[60:61], v[130:131], 0, v[60:61]
	global_store_short v[70:71], v32, off offset:64
	v_cvt_pk_bf16_f32 v32, v39, s0
	global_store_short v[60:61], v78, off
	v_or_b32_e32 v78, 0x5a, v128
	global_store_short v[54:55], v32, off offset:64
	v_cvt_pk_bf16_f32 v32, v40, s0
	v_ashrrev_i32_e32 v79, 31, v78
	global_store_short v[72:73], v32, off offset:64
	v_cvt_pk_bf16_f32 v32, v41, s0
	v_lshlrev_b64 v[78:79], 12, v[78:79]
	global_store_short v[56:57], v32, off offset:64
	v_cvt_pk_bf16_f32 v32, v42, s0
	v_cvt_pk_bf16_f32 v62, v62, s0
	v_lshl_add_u64 v[78:79], v[130:131], 0, v[78:79]
	global_store_short v[74:75], v32, off offset:64
	v_cvt_pk_bf16_f32 v32, v43, s0
	global_store_short v[78:79], v62, off
	v_or_b32_e32 v62, 0x5b, v128
	global_store_short v[58:59], v32, off offset:64
	v_cvt_pk_bf16_f32 v32, v44, s0
	v_cvt_pk_bf16_f32 v80, v63, s0
	v_ashrrev_i32_e32 v63, 31, v62
	global_store_short v[76:77], v32, off offset:64
	v_cvt_pk_bf16_f32 v32, v45, s0
	v_lshlrev_b64 v[62:63], 12, v[62:63]
	global_store_short v[60:61], v32, off offset:64
	v_cvt_pk_bf16_f32 v32, v46, s0
	v_lshl_add_u64 v[62:63], v[130:131], 0, v[62:63]
	global_store_short v[78:79], v32, off offset:64
	v_cvt_pk_bf16_f32 v32, v47, s0
	global_store_short v[62:63], v32, off offset:64
	v_or_b32_e32 v32, 0x60, v128
	v_ashrrev_i32_e32 v33, 31, v32
	v_lshlrev_b64 v[32:33], 12, v[32:33]
	v_cvt_pk_bf16_f32 v16, v16, s0
	v_lshl_add_u64 v[32:33], v[130:131], 0, v[32:33]
	global_store_short v[32:33], v16, off
	v_or_b32_e32 v16, 0x61, v128
	v_cvt_pk_bf16_f32 v34, v17, s0
	v_ashrrev_i32_e32 v17, 31, v16
	v_lshlrev_b64 v[16:17], 12, v[16:17]
	v_lshl_add_u64 v[16:17], v[130:131], 0, v[16:17]
	global_store_short v[16:17], v34, off
	v_or_b32_e32 v34, 0x62, v128
	v_ashrrev_i32_e32 v35, 31, v34
	v_lshlrev_b64 v[34:35], 12, v[34:35]
	v_cvt_pk_bf16_f32 v18, v18, s0
	v_lshl_add_u64 v[34:35], v[130:131], 0, v[34:35]
	global_store_short v[34:35], v18, off
	v_or_b32_e32 v18, 0x63, v128
	v_cvt_pk_bf16_f32 v36, v19, s0
	v_ashrrev_i32_e32 v19, 31, v18
	v_lshlrev_b64 v[18:19], 12, v[18:19]
	v_lshl_add_u64 v[18:19], v[130:131], 0, v[18:19]
	global_store_short v[18:19], v36, off
	v_or_b32_e32 v36, 0x68, v128
	v_ashrrev_i32_e32 v37, 31, v36
	v_lshlrev_b64 v[36:37], 12, v[36:37]
	v_cvt_pk_bf16_f32 v20, v20, s0
	v_lshl_add_u64 v[36:37], v[130:131], 0, v[36:37]
	global_store_short v[36:37], v20, off
	v_or_b32_e32 v20, 0x69, v128
	v_cvt_pk_bf16_f32 v38, v21, s0
	v_ashrrev_i32_e32 v21, 31, v20
	v_lshlrev_b64 v[20:21], 12, v[20:21]
	v_lshl_add_u64 v[20:21], v[130:131], 0, v[20:21]
	global_store_short v[20:21], v38, off
	v_or_b32_e32 v38, 0x6a, v128
	v_ashrrev_i32_e32 v39, 31, v38
	v_lshlrev_b64 v[38:39], 12, v[38:39]
	v_cvt_pk_bf16_f32 v22, v22, s0
	v_lshl_add_u64 v[38:39], v[130:131], 0, v[38:39]
	global_store_short v[38:39], v22, off
	v_or_b32_e32 v22, 0x6b, v128
	v_cvt_pk_bf16_f32 v40, v23, s0
	v_ashrrev_i32_e32 v23, 31, v22
	v_lshlrev_b64 v[22:23], 12, v[22:23]
	v_lshl_add_u64 v[22:23], v[130:131], 0, v[22:23]
	global_store_short v[22:23], v40, off
	v_or_b32_e32 v40, 0x70, v128
	v_ashrrev_i32_e32 v41, 31, v40
	v_lshlrev_b64 v[40:41], 12, v[40:41]
	v_cvt_pk_bf16_f32 v24, v24, s0
	v_lshl_add_u64 v[40:41], v[130:131], 0, v[40:41]
	global_store_short v[40:41], v24, off
	v_or_b32_e32 v24, 0x71, v128
	v_cvt_pk_bf16_f32 v42, v25, s0
	v_ashrrev_i32_e32 v25, 31, v24
	v_lshlrev_b64 v[24:25], 12, v[24:25]
	v_lshl_add_u64 v[24:25], v[130:131], 0, v[24:25]
	global_store_short v[24:25], v42, off
	v_or_b32_e32 v42, 0x72, v128
	v_ashrrev_i32_e32 v43, 31, v42
	v_lshlrev_b64 v[42:43], 12, v[42:43]
	v_cvt_pk_bf16_f32 v26, v26, s0
	v_lshl_add_u64 v[42:43], v[130:131], 0, v[42:43]
	global_store_short v[42:43], v26, off
	v_or_b32_e32 v26, 0x73, v128
	v_cvt_pk_bf16_f32 v44, v27, s0
	v_ashrrev_i32_e32 v27, 31, v26
	v_lshlrev_b64 v[26:27], 12, v[26:27]
	v_lshl_add_u64 v[26:27], v[130:131], 0, v[26:27]
	global_store_short v[26:27], v44, off
	v_or_b32_e32 v44, 0x78, v128
	v_cvt_pk_bf16_f32 v0, v0, s0
	v_ashrrev_i32_e32 v45, 31, v44
	global_store_short v[32:33], v0, off offset:64
	v_cvt_pk_bf16_f32 v0, v1, s0
	v_lshlrev_b64 v[44:45], 12, v[44:45]
	global_store_short v[16:17], v0, off offset:64
	v_cvt_pk_bf16_f32 v0, v2, s0
	v_cvt_pk_bf16_f32 v28, v28, s0
	v_lshl_add_u64 v[44:45], v[130:131], 0, v[44:45]
	global_store_short v[34:35], v0, off offset:64
	v_cvt_pk_bf16_f32 v0, v3, s0
	global_store_short v[44:45], v28, off
	v_or_b32_e32 v28, 0x79, v128
	global_store_short v[18:19], v0, off offset:64
	v_cvt_pk_bf16_f32 v0, v4, s0
	v_cvt_pk_bf16_f32 v46, v29, s0
	v_ashrrev_i32_e32 v29, 31, v28
	global_store_short v[36:37], v0, off offset:64
	v_cvt_pk_bf16_f32 v0, v5, s0
	v_lshlrev_b64 v[28:29], 12, v[28:29]
	global_store_short v[20:21], v0, off offset:64
	v_cvt_pk_bf16_f32 v0, v6, s0
	v_lshl_add_u64 v[28:29], v[130:131], 0, v[28:29]
	global_store_short v[38:39], v0, off offset:64
	v_cvt_pk_bf16_f32 v0, v7, s0
	global_store_short v[28:29], v46, off
	v_or_b32_e32 v46, 0x7a, v128
	global_store_short v[22:23], v0, off offset:64
	v_cvt_pk_bf16_f32 v0, v8, s0
	v_ashrrev_i32_e32 v47, 31, v46
	global_store_short v[40:41], v0, off offset:64
	v_cvt_pk_bf16_f32 v0, v9, s0
	v_lshlrev_b64 v[46:47], 12, v[46:47]
	global_store_short v[24:25], v0, off offset:64
	v_cvt_pk_bf16_f32 v0, v10, s0
	v_cvt_pk_bf16_f32 v30, v30, s0
	v_lshl_add_u64 v[46:47], v[130:131], 0, v[46:47]
	global_store_short v[42:43], v0, off offset:64
	v_cvt_pk_bf16_f32 v0, v11, s0
	global_store_short v[46:47], v30, off
	v_or_b32_e32 v30, 0x7b, v128
	global_store_short v[26:27], v0, off offset:64
	v_cvt_pk_bf16_f32 v0, v12, s0
	v_cvt_pk_bf16_f32 v48, v31, s0
	v_ashrrev_i32_e32 v31, 31, v30
	global_store_short v[44:45], v0, off offset:64
	v_cvt_pk_bf16_f32 v0, v13, s0
	v_lshlrev_b64 v[30:31], 12, v[30:31]
	global_store_short v[28:29], v0, off offset:64
	v_cvt_pk_bf16_f32 v0, v14, s0
	v_lshl_add_u64 v[30:31], v[130:131], 0, v[30:31]
	global_store_short v[46:47], v0, off offset:64
	v_cvt_pk_bf16_f32 v0, v15, s0
	global_store_short v[126:127], v129, off
	global_store_short v[94:95], v112, off
	global_store_short v[62:63], v80, off
	global_store_short v[30:31], v48, off
	global_store_short v[30:31], v0, off offset:64
	s_cbranch_scc0 .LBB0_36

.LBB0_96:
	v_add_u32_e32 v186, v200, v202
	ds_read_b128 v[208:211], v186 offset:24576
	ds_read_b128 v[212:215], v186 offset:26624
	ds_read_b128 v[216:219], v186 offset:28672
	ds_read_b128 v[238:241], v186 offset:30720
	v_add_u32_e32 v205, v203, v202
	ds_read_b128 v[244:247], v205 offset:40960
	ds_read_b128 v[248:251], v205 offset:43008
	v_mfma_f32_32x32x16_bf16 v[112:127], v[148:151], v[136:139], v[112:127]
	v_add_u32_e32 v206, v200, v204
	v_add_u32_e32 v207, v203, v204
	v_mfma_f32_32x32x16_bf16 v[96:111], v[148:151], v[132:135], v[96:111]
	v_mfma_f32_32x32x16_bf16 v[80:95], v[144:147], v[136:139], v[80:95]
	v_mfma_f32_32x32x16_bf16 v[64:79], v[144:147], v[132:135], v[64:79]
	v_mfma_f32_32x32x16_bf16 v[48:63], v[140:143], v[136:139], v[48:63]
	v_mfma_f32_32x32x16_bf16 v[32:47], v[140:143], v[132:135], v[32:47]
	v_mfma_f32_32x32x16_bf16 v[16:31], v[128:131], v[136:139], v[16:31]
	v_mfma_f32_32x32x16_bf16 v[0:15], v[128:131], v[132:135], v[0:15]
	ds_read_b128 v[128:131], v206 offset:24576
	ds_read_b128 v[132:135], v206 offset:26624
	ds_read_b128 v[136:139], v206 offset:28672
	ds_read_b128 v[140:143], v206 offset:30720
	ds_read_b128 v[144:147], v207 offset:40960
	ds_read_b128 v[148:151], v207 offset:43008
	s_waitcnt lgkmcnt(7)
	v_mfma_f32_32x32x16_bf16 v[112:127], v[208:211], v[244:247], v[112:127]
	s_waitcnt lgkmcnt(6)
	v_mfma_f32_32x32x16_bf16 v[96:111], v[208:211], v[248:251], v[96:111]
	v_mfma_f32_32x32x16_bf16 v[80:95], v[212:215], v[244:247], v[80:95]
	v_mfma_f32_32x32x16_bf16 v[64:79], v[212:215], v[248:251], v[64:79]
	v_mfma_f32_32x32x16_bf16 v[48:63], v[216:219], v[244:247], v[48:63]
	v_mfma_f32_32x32x16_bf16 v[32:47], v[216:219], v[248:251], v[32:47]
	v_mfma_f32_32x32x16_bf16 v[16:31], v[238:241], v[244:247], v[16:31]
	v_mfma_f32_32x32x16_bf16 v[0:15], v[238:241], v[248:251], v[0:15]
	s_getreg_b32 s39, hwreg(HW_REG_HW_ID, 0, 4)
	s_bitcmp1_b32 s39, 0
	s_cbranch_scc1 .Lgp2
	s_setprio 0
.Lgp2:
	s_waitcnt vmcnt(2)
	ds_write_b128 v201, v[164:167] offset:12288
	v_lshl_add_u64 v[164:165], v[198:199], 0, s[0:1]
	ds_write_b128 v201, v[152:155]
	v_add_co_u32_e32 v152, vcc, s92, v164
	ds_write_b128 v201, v[156:159] offset:4096
	s_nop 0
	v_addc_co_u32_e32 v153, vcc, 0, v165, vcc
	v_add_co_u32_e32 v156, vcc, s93, v164
	ds_write_b128 v201, v[160:163] offset:8192
	s_nop 0
	v_addc_co_u32_e32 v157, vcc, 0, v165, vcc
	v_add_co_u32_e32 v160, vcc, s88, v164
	s_waitcnt vmcnt(0)
	ds_write_b128 v201, v[172:175] offset:20480
	v_addc_co_u32_e32 v161, vcc, 0, v165, vcc
	v_add_co_u32_e32 v164, vcc, s89, v164
	v_lshl_add_u64 v[172:173], v[196:197], 0, s[0:1]
	s_nop 0
	v_addc_co_u32_e32 v165, vcc, 0, v165, vcc
	s_mov_b32 s8, 0x2100000
	ds_write_b128 v201, v[168:171] offset:16384
	v_add_co_u32_e32 v168, vcc, s8, v172
	s_mov_b32 s8, 0x2140000
	s_nop 0
	v_addc_co_u32_e32 v169, vcc, 0, v173, vcc
	v_add_co_u32_e32 v172, vcc, s8, v172
	global_load_dwordx4 v[152:155], v[152:153], off offset:192
	s_nop 0
	v_addc_co_u32_e32 v173, vcc, 0, v173, vcc
	global_load_dwordx4 v[156:159], v[156:157], off offset:192
	s_nop 0
	global_load_dwordx4 v[160:163], v[160:161], off offset:192
	s_nop 0
	global_load_dwordx4 v[164:167], v[164:165], off offset:192
	s_nop 0
	global_load_dwordx4 v[168:171], v[168:169], off offset:192
	s_nop 0
	global_load_dwordx4 v[172:175], v[172:173], off offset:192
	s_waitcnt lgkmcnt(0)
	s_barrier
	s_setprio 1
	ds_read_b128 v[208:211], v186
	ds_read_b128 v[212:215], v186 offset:2048
	ds_read_b128 v[216:219], v186 offset:4096
	ds_read_b128 v[238:241], v186 offset:6144
	ds_read_b128 v[244:247], v205 offset:16384
	ds_read_b128 v[248:251], v205 offset:18432
	v_mfma_f32_32x32x16_bf16 v[112:127], v[128:131], v[144:147], v[112:127]
	v_mfma_f32_32x32x16_bf16 v[96:111], v[128:131], v[148:151], v[96:111]
	v_mfma_f32_32x32x16_bf16 v[80:95], v[132:135], v[144:147], v[80:95]
	v_mfma_f32_32x32x16_bf16 v[64:79], v[132:135], v[148:151], v[64:79]
	v_mfma_f32_32x32x16_bf16 v[48:63], v[136:139], v[144:147], v[48:63]
	v_mfma_f32_32x32x16_bf16 v[32:47], v[136:139], v[148:151], v[32:47]
	v_mfma_f32_32x32x16_bf16 v[16:31], v[140:143], v[144:147], v[16:31]
	v_mfma_f32_32x32x16_bf16 v[0:15], v[140:143], v[148:151], v[0:15]
	ds_read_b128 v[148:151], v206
	ds_read_b128 v[144:147], v206 offset:2048
	ds_read_b128 v[140:143], v206 offset:4096
	ds_read_b128 v[128:131], v206 offset:6144
	ds_read_b128 v[136:139], v207 offset:16384
	ds_read_b128 v[132:135], v207 offset:18432
	s_waitcnt lgkmcnt(7)
	v_mfma_f32_32x32x16_bf16 v[112:127], v[208:211], v[244:247], v[112:127]
	s_waitcnt lgkmcnt(6)
	v_mfma_f32_32x32x16_bf16 v[96:111], v[208:211], v[248:251], v[96:111]
	v_mfma_f32_32x32x16_bf16 v[80:95], v[212:215], v[244:247], v[80:95]
	v_mfma_f32_32x32x16_bf16 v[64:79], v[212:215], v[248:251], v[64:79]
	v_mfma_f32_32x32x16_bf16 v[48:63], v[216:219], v[244:247], v[48:63]
	v_mfma_f32_32x32x16_bf16 v[32:47], v[216:219], v[248:251], v[32:47]
	v_mfma_f32_32x32x16_bf16 v[16:31], v[238:241], v[244:247], v[16:31]
	v_mfma_f32_32x32x16_bf16 v[0:15], v[238:241], v[248:251], v[0:15]
	s_getreg_b32 s39, hwreg(HW_REG_HW_ID, 0, 4)
	s_bitcmp1_b32 s39, 0
	s_cbranch_scc1 .Lgp3
	s_setprio 0
.Lgp3:
	s_min_u32 s8, s3, 60
	s_lshl_b32 s66, s8, 6
	s_add_i32 s8, s66, 0xc0
	s_mov_b32 s9, s67
	s_waitcnt vmcnt(5)
	ds_write_b128 v201, v[152:155] offset:24576
	s_waitcnt vmcnt(4)
	ds_write_b128 v201, v[156:159] offset:28672
	s_waitcnt vmcnt(3)
	ds_write_b128 v201, v[160:163] offset:32768
	s_waitcnt vmcnt(2)
	ds_write_b128 v201, v[164:167] offset:36864
	s_waitcnt vmcnt(1)
	ds_write_b128 v201, v[168:171] offset:40960
	s_waitcnt vmcnt(0)
	ds_write_b128 v201, v[172:175] offset:45056
	v_lshl_add_u64 v[152:153], v[176:177], 0, s[66:67]
	v_lshl_add_u64 v[156:157], v[180:181], 0, s[8:9]
	v_lshl_add_u64 v[160:161], v[182:183], 0, s[8:9]
	v_lshl_add_u64 v[164:165], v[192:193], 0, s[8:9]
	v_lshl_add_u64 v[168:169], v[178:179], 0, s[66:67]
	v_lshl_add_u64 v[172:173], v[194:195], 0, s[8:9]
	global_load_dwordx4 v[152:155], v[152:153], off offset:192
	s_add_i32 s3, s3, 2
	global_load_dwordx4 v[156:159], v[156:157], off
	s_add_u32 s0, s0, 0x80
	global_load_dwordx4 v[160:163], v[160:161], off
	s_addc_u32 s1, s1, 0
	global_load_dwordx4 v[164:167], v[164:165], off
	s_cmpk_lg_i32 s0, 0xf80
	global_load_dwordx4 v[168:171], v[168:169], off offset:192
	s_nop 0
	global_load_dwordx4 v[172:175], v[172:173], off
	s_waitcnt lgkmcnt(0)
	s_barrier
	s_setprio 1
	s_cbranch_scc1 .LBB0_96
	s_waitcnt vmcnt(5)
	ds_read_b128 v[152:155], v186 offset:24576
	s_waitcnt vmcnt(4)
	ds_read_b128 v[156:159], v186 offset:26624
	s_waitcnt vmcnt(3)
	ds_read_b128 v[160:163], v186 offset:28672
	s_waitcnt vmcnt(2)
	ds_read_b128 v[164:167], v186 offset:30720
	s_waitcnt vmcnt(1)
	ds_read_b128 v[168:171], v205 offset:40960
	s_waitcnt vmcnt(0)
	ds_read_b128 v[172:175], v205 offset:43008
	v_mfma_f32_32x32x16_bf16 v[112:127], v[148:151], v[136:139], v[112:127]
	v_mfma_f32_32x32x16_bf16 v[96:111], v[148:151], v[132:135], v[96:111]
	v_mfma_f32_32x32x16_bf16 v[80:95], v[144:147], v[136:139], v[80:95]
	v_mfma_f32_32x32x16_bf16 v[64:79], v[144:147], v[132:135], v[64:79]
	v_mfma_f32_32x32x16_bf16 v[48:63], v[140:143], v[136:139], v[48:63]
	v_mfma_f32_32x32x16_bf16 v[32:47], v[140:143], v[132:135], v[32:47]
	v_mfma_f32_32x32x16_bf16 v[16:31], v[128:131], v[136:139], v[16:31]
	v_mfma_f32_32x32x16_bf16 v[0:15], v[128:131], v[132:135], v[0:15]
	ds_read_b128 v[128:131], v206 offset:24576
	ds_read_b128 v[132:135], v206 offset:26624
	ds_read_b128 v[136:139], v206 offset:28672
	ds_read_b128 v[140:143], v206 offset:30720
	ds_read_b128 v[144:147], v207 offset:40960
	ds_read_b128 v[148:151], v207 offset:43008
	s_waitcnt lgkmcnt(7)
	v_mfma_f32_32x32x16_bf16 v[112:127], v[152:155], v[168:171], v[112:127]
	s_waitcnt lgkmcnt(6)
	v_mfma_f32_32x32x16_bf16 v[96:111], v[152:155], v[172:175], v[96:111]
	v_mfma_f32_32x32x16_bf16 v[80:95], v[156:159], v[168:171], v[80:95]
	v_mfma_f32_32x32x16_bf16 v[64:79], v[156:159], v[172:175], v[64:79]
	v_mfma_f32_32x32x16_bf16 v[48:63], v[160:163], v[168:171], v[48:63]
	v_mfma_f32_32x32x16_bf16 v[32:47], v[160:163], v[172:175], v[32:47]
	v_mfma_f32_32x32x16_bf16 v[16:31], v[164:167], v[168:171], v[16:31]
	v_mfma_f32_32x32x16_bf16 v[0:15], v[164:167], v[172:175], v[0:15]
	s_waitcnt lgkmcnt(1)
	v_mfma_f32_32x32x16_bf16 v[112:127], v[128:131], v[144:147], v[112:127]
	s_mov_b64 s[0:1], -1
	s_cmp_gt_i32 s2, 3
	s_waitcnt lgkmcnt(0)
	s_barrier
	v_mfma_f32_32x32x16_bf16 v[96:111], v[128:131], v[148:151], v[96:111]
	v_mfma_f32_32x32x16_bf16 v[80:95], v[132:135], v[144:147], v[80:95]
	v_mfma_f32_32x32x16_bf16 v[64:79], v[132:135], v[148:151], v[64:79]
	v_mfma_f32_32x32x16_bf16 v[48:63], v[136:139], v[144:147], v[48:63]
	v_mfma_f32_32x32x16_bf16 v[32:47], v[136:139], v[148:151], v[32:47]
	v_mfma_f32_32x32x16_bf16 v[16:31], v[140:143], v[144:147], v[16:31]
	v_mfma_f32_32x32x16_bf16 v[0:15], v[140:143], v[148:151], v[0:15]
	s_cbranch_scc1 .LBB0_99
	s_andn2_b64 vcc, exec, s[0:1]
	s_cbranch_vccnz .LBB0_94
	s_branch .LBB0_126

.Lgp4:
	s_waitcnt vmcnt(2)
	ds_write_b128 v201, v[164:167] offset:12288
	v_lshl_add_u64 v[164:165], v[198:199], 0, s[8:9]
	ds_write_b128 v201, v[152:155]
	v_add_co_u32_e32 v152, vcc, s92, v164
	ds_write_b128 v201, v[156:159] offset:4096
	s_nop 0
	v_addc_co_u32_e32 v153, vcc, 0, v165, vcc
	v_add_co_u32_e32 v156, vcc, s93, v164
	ds_write_b128 v201, v[160:163] offset:8192
	s_nop 0
	v_addc_co_u32_e32 v157, vcc, 0, v165, vcc
	v_add_co_u32_e32 v160, vcc, s88, v164
	s_waitcnt vmcnt(0)
	ds_write_b128 v201, v[172:175] offset:20480
	v_addc_co_u32_e32 v161, vcc, 0, v165, vcc
	v_add_co_u32_e32 v164, vcc, s89, v164
	v_lshl_add_u64 v[172:173], v[196:197], 0, s[8:9]
	s_nop 0
	v_addc_co_u32_e32 v165, vcc, 0, v165, vcc
	s_mov_b32 s16, 0x1900000
	ds_write_b128 v201, v[168:171] offset:16384
	v_add_co_u32_e32 v168, vcc, s16, v172
	s_mov_b32 s16, 0x1940000
	s_nop 0
	v_addc_co_u32_e32 v169, vcc, 0, v173, vcc
	v_add_co_u32_e32 v172, vcc, s16, v172
	global_load_dwordx4 v[152:155], v[152:153], off offset:192
	s_nop 0
	v_addc_co_u32_e32 v173, vcc, 0, v173, vcc
	global_load_dwordx4 v[156:159], v[156:157], off offset:192
	s_nop 0
	global_load_dwordx4 v[160:163], v[160:161], off offset:192
	s_nop 0
	global_load_dwordx4 v[164:167], v[164:165], off offset:192
	s_nop 0
	global_load_dwordx4 v[168:171], v[168:169], off offset:192
	s_nop 0
	global_load_dwordx4 v[172:175], v[172:173], off offset:192
	s_waitcnt lgkmcnt(0)
	s_barrier
	s_setprio 1
	ds_read_b128 v[208:211], v186
	ds_read_b128 v[212:215], v186 offset:2048
	ds_read_b128 v[216:219], v186 offset:4096
	ds_read_b128 v[238:241], v186 offset:6144
	ds_read_b128 v[244:247], v205 offset:16384
	ds_read_b128 v[248:251], v205 offset:18432
	v_mfma_f32_32x32x16_bf16 v[112:127], v[128:131], v[144:147], v[112:127]
	v_mfma_f32_32x32x16_bf16 v[96:111], v[128:131], v[148:151], v[96:111]
	v_mfma_f32_32x32x16_bf16 v[80:95], v[132:135], v[144:147], v[80:95]
	v_mfma_f32_32x32x16_bf16 v[64:79], v[132:135], v[148:151], v[64:79]
	v_mfma_f32_32x32x16_bf16 v[48:63], v[136:139], v[144:147], v[48:63]
	v_mfma_f32_32x32x16_bf16 v[32:47], v[136:139], v[148:151], v[32:47]
	v_mfma_f32_32x32x16_bf16 v[16:31], v[140:143], v[144:147], v[16:31]
	v_mfma_f32_32x32x16_bf16 v[0:15], v[140:143], v[148:151], v[0:15]
	ds_read_b128 v[140:143], v206
	ds_read_b128 v[136:139], v206 offset:2048
	ds_read_b128 v[132:135], v206 offset:4096
	ds_read_b128 v[128:131], v206 offset:6144
	ds_read_b128 v[148:151], v207 offset:16384
	ds_read_b128 v[144:147], v207 offset:18432
	s_waitcnt lgkmcnt(7)
	v_mfma_f32_32x32x16_bf16 v[112:127], v[208:211], v[244:247], v[112:127]
	s_waitcnt lgkmcnt(6)
	v_mfma_f32_32x32x16_bf16 v[96:111], v[208:211], v[248:251], v[96:111]
	v_mfma_f32_32x32x16_bf16 v[80:95], v[212:215], v[244:247], v[80:95]
	v_mfma_f32_32x32x16_bf16 v[64:79], v[212:215], v[248:251], v[64:79]
	v_mfma_f32_32x32x16_bf16 v[48:63], v[216:219], v[244:247], v[48:63]
	v_mfma_f32_32x32x16_bf16 v[32:47], v[216:219], v[248:251], v[32:47]
	v_mfma_f32_32x32x16_bf16 v[16:31], v[238:241], v[244:247], v[16:31]
	v_mfma_f32_32x32x16_bf16 v[0:15], v[238:241], v[248:251], v[0:15]
	s_getreg_b32 s39, hwreg(HW_REG_HW_ID, 0, 4)
	s_bitcmp1_b32 s39, 0
	s_cbranch_scc1 .Lgp5
	s_setprio 0

.LBB0_234:
	v_add_u32_e32 v186, v198, v200
	ds_read_b128 v[206:209], v186 offset:24576
	ds_read_b128 v[210:213], v186 offset:26624
	ds_read_b128 v[214:217], v186 offset:28672
	ds_read_b128 v[238:241], v186 offset:30720
	v_add_u32_e32 v203, v201, v200
	ds_read_b128 v[244:247], v203 offset:40960
	ds_read_b128 v[248:251], v203 offset:43008
	v_mfma_f32_32x32x16_bf16 v[112:127], v[148:151], v[136:139], v[112:127]
	v_add_u32_e32 v204, v198, v202
	v_add_u32_e32 v205, v201, v202
	v_mfma_f32_32x32x16_bf16 v[96:111], v[148:151], v[132:135], v[96:111]
	v_mfma_f32_32x32x16_bf16 v[80:95], v[144:147], v[136:139], v[80:95]
	v_mfma_f32_32x32x16_bf16 v[64:79], v[144:147], v[132:135], v[64:79]
	v_mfma_f32_32x32x16_bf16 v[48:63], v[140:143], v[136:139], v[48:63]
	v_mfma_f32_32x32x16_bf16 v[32:47], v[140:143], v[132:135], v[32:47]
	v_mfma_f32_32x32x16_bf16 v[16:31], v[128:131], v[136:139], v[16:31]
	v_mfma_f32_32x32x16_bf16 v[0:15], v[128:131], v[132:135], v[0:15]
	ds_read_b128 v[128:131], v204 offset:24576
	ds_read_b128 v[132:135], v204 offset:26624
	ds_read_b128 v[136:139], v204 offset:28672
	ds_read_b128 v[140:143], v204 offset:30720
	ds_read_b128 v[144:147], v205 offset:40960
	ds_read_b128 v[148:151], v205 offset:43008
	s_waitcnt lgkmcnt(7)
	v_mfma_f32_32x32x16_bf16 v[112:127], v[206:209], v[244:247], v[112:127]
	s_waitcnt lgkmcnt(6)
	v_mfma_f32_32x32x16_bf16 v[96:111], v[206:209], v[248:251], v[96:111]
	v_mfma_f32_32x32x16_bf16 v[80:95], v[210:213], v[244:247], v[80:95]
	v_mfma_f32_32x32x16_bf16 v[64:79], v[210:213], v[248:251], v[64:79]
	v_mfma_f32_32x32x16_bf16 v[48:63], v[214:217], v[244:247], v[48:63]
	v_mfma_f32_32x32x16_bf16 v[32:47], v[214:217], v[248:251], v[32:47]
	v_mfma_f32_32x32x16_bf16 v[16:31], v[238:241], v[244:247], v[16:31]
	v_mfma_f32_32x32x16_bf16 v[0:15], v[238:241], v[248:251], v[0:15]
	s_getreg_b32 s39, hwreg(HW_REG_HW_ID, 0, 4)
	s_bitcmp1_b32 s39, 0
	s_cbranch_scc1 .Lgp6
	s_setprio 0
.Lgp6:
	s_waitcnt vmcnt(2)
	ds_write_b128 v199, v[164:167] offset:12288
	v_lshl_add_u64 v[164:165], v[196:197], 0, s[0:1]
	ds_write_b128 v199, v[152:155]
	v_add_co_u32_e32 v152, vcc, s92, v164
	ds_write_b128 v199, v[156:159] offset:4096
	s_nop 0
	v_addc_co_u32_e32 v153, vcc, 0, v165, vcc
	v_add_co_u32_e32 v156, vcc, s93, v164
	ds_write_b128 v199, v[160:163] offset:8192
	s_nop 0
	v_addc_co_u32_e32 v157, vcc, 0, v165, vcc
	v_add_co_u32_e32 v160, vcc, s88, v164
	s_waitcnt vmcnt(0)
	ds_write_b128 v199, v[172:175] offset:20480
	v_addc_co_u32_e32 v161, vcc, 0, v165, vcc
	v_add_co_u32_e32 v164, vcc, s89, v164
	v_lshl_add_u64 v[172:173], v[178:179], 0, s[0:1]
	s_nop 0
	v_addc_co_u32_e32 v165, vcc, 0, v165, vcc
	ds_write_b128 v199, v[168:171] offset:16384
	global_load_dwordx4 v[168:171], v[172:173], off offset:192
	v_add_co_u32_e32 v172, vcc, s78, v172
	global_load_dwordx4 v[152:155], v[152:153], off offset:192
	s_nop 0
	v_addc_co_u32_e32 v173, vcc, 0, v173, vcc
	global_load_dwordx4 v[156:159], v[156:157], off offset:192
	s_nop 0
	global_load_dwordx4 v[160:163], v[160:161], off offset:192
	s_nop 0
	global_load_dwordx4 v[164:167], v[164:165], off offset:192
	s_nop 0
	global_load_dwordx4 v[172:175], v[172:173], off offset:192
	s_waitcnt lgkmcnt(0)
	s_barrier
	s_setprio 1
	ds_read_b128 v[206:209], v186
	ds_read_b128 v[210:213], v186 offset:2048
	ds_read_b128 v[214:217], v186 offset:4096
	ds_read_b128 v[238:241], v186 offset:6144
	ds_read_b128 v[244:247], v203 offset:16384
	ds_read_b128 v[248:251], v203 offset:18432
	v_mfma_f32_32x32x16_bf16 v[112:127], v[128:131], v[144:147], v[112:127]
	v_mfma_f32_32x32x16_bf16 v[96:111], v[128:131], v[148:151], v[96:111]
	v_mfma_f32_32x32x16_bf16 v[80:95], v[132:135], v[144:147], v[80:95]
	v_mfma_f32_32x32x16_bf16 v[64:79], v[132:135], v[148:151], v[64:79]
	v_mfma_f32_32x32x16_bf16 v[48:63], v[136:139], v[144:147], v[48:63]
	v_mfma_f32_32x32x16_bf16 v[32:47], v[136:139], v[148:151], v[32:47]
	v_mfma_f32_32x32x16_bf16 v[16:31], v[140:143], v[144:147], v[16:31]
	v_mfma_f32_32x32x16_bf16 v[0:15], v[140:143], v[148:151], v[0:15]
	ds_read_b128 v[148:151], v204
	ds_read_b128 v[144:147], v204 offset:2048
	ds_read_b128 v[140:143], v204 offset:4096
	ds_read_b128 v[128:131], v204 offset:6144
	ds_read_b128 v[136:139], v205 offset:16384
	ds_read_b128 v[132:135], v205 offset:18432
	s_waitcnt lgkmcnt(7)
	v_mfma_f32_32x32x16_bf16 v[112:127], v[206:209], v[244:247], v[112:127]
	s_waitcnt lgkmcnt(6)
	v_mfma_f32_32x32x16_bf16 v[96:111], v[206:209], v[248:251], v[96:111]
	v_mfma_f32_32x32x16_bf16 v[80:95], v[210:213], v[244:247], v[80:95]
	v_mfma_f32_32x32x16_bf16 v[64:79], v[210:213], v[248:251], v[64:79]
	v_mfma_f32_32x32x16_bf16 v[48:63], v[214:217], v[244:247], v[48:63]
	v_mfma_f32_32x32x16_bf16 v[32:47], v[214:217], v[248:251], v[32:47]
	v_mfma_f32_32x32x16_bf16 v[16:31], v[238:241], v[244:247], v[16:31]
	v_mfma_f32_32x32x16_bf16 v[0:15], v[238:241], v[248:251], v[0:15]
	s_getreg_b32 s39, hwreg(HW_REG_HW_ID, 0, 4)
	s_bitcmp1_b32 s39, 0
	s_cbranch_scc1 .Lgp7
	s_setprio 0
.Lgp7:
	s_min_u32 s8, s7, 60
	s_lshl_b32 s66, s8, 6
	s_add_i32 s8, s66, 0xc0
	s_mov_b32 s9, s67
	s_waitcnt vmcnt(4)
	ds_write_b128 v199, v[152:155] offset:24576
	s_waitcnt vmcnt(3)
	ds_write_b128 v199, v[156:159] offset:28672
	s_waitcnt vmcnt(2)
	ds_write_b128 v199, v[160:163] offset:32768
	s_waitcnt vmcnt(1)
	ds_write_b128 v199, v[164:167] offset:36864
	ds_write_b128 v199, v[168:171] offset:40960
	s_waitcnt vmcnt(0)
	ds_write_b128 v199, v[172:175] offset:45056
	v_lshl_add_u64 v[152:153], v[176:177], 0, s[66:67]
	v_lshl_add_u64 v[156:157], v[180:181], 0, s[8:9]
	v_lshl_add_u64 v[160:161], v[182:183], 0, s[8:9]
	v_lshl_add_u64 v[164:165], v[192:193], 0, s[8:9]
	v_lshl_add_u64 v[168:169], v[178:179], 0, s[66:67]
	v_lshl_add_u64 v[172:173], v[194:195], 0, s[8:9]
	global_load_dwordx4 v[152:155], v[152:153], off offset:192
	s_add_i32 s7, s7, 2
	global_load_dwordx4 v[156:159], v[156:157], off
	s_add_u32 s0, s0, 0x80
	global_load_dwordx4 v[160:163], v[160:161], off
	s_addc_u32 s1, s1, 0
	global_load_dwordx4 v[164:167], v[164:165], off
	s_cmpk_lg_i32 s0, 0xf80
	global_load_dwordx4 v[168:171], v[168:169], off offset:192
	s_nop 0
	global_load_dwordx4 v[172:175], v[172:173], off
	s_waitcnt lgkmcnt(0)
	s_barrier
	s_setprio 1
	s_cbranch_scc1 .LBB0_234
	s_waitcnt vmcnt(5)
	ds_read_b128 v[152:155], v186 offset:24576
	s_waitcnt vmcnt(4)
	ds_read_b128 v[156:159], v186 offset:26624
	s_waitcnt vmcnt(3)
	ds_read_b128 v[160:163], v186 offset:28672
	s_waitcnt vmcnt(2)
	ds_read_b128 v[164:167], v186 offset:30720
	s_waitcnt vmcnt(1)
	ds_read_b128 v[168:171], v203 offset:40960
	s_waitcnt vmcnt(0)
	ds_read_b128 v[172:175], v203 offset:43008
	v_mfma_f32_32x32x16_bf16 v[112:127], v[148:151], v[136:139], v[112:127]
	v_mfma_f32_32x32x16_bf16 v[96:111], v[148:151], v[132:135], v[96:111]
	v_mfma_f32_32x32x16_bf16 v[80:95], v[144:147], v[136:139], v[80:95]
	v_mfma_f32_32x32x16_bf16 v[64:79], v[144:147], v[132:135], v[64:79]
	v_mfma_f32_32x32x16_bf16 v[48:63], v[140:143], v[136:139], v[48:63]
	v_mfma_f32_32x32x16_bf16 v[32:47], v[140:143], v[132:135], v[32:47]
	v_mfma_f32_32x32x16_bf16 v[16:31], v[128:131], v[136:139], v[16:31]
	v_mfma_f32_32x32x16_bf16 v[0:15], v[128:131], v[132:135], v[0:15]
	ds_read_b128 v[128:131], v204 offset:24576
	ds_read_b128 v[132:135], v204 offset:26624
	ds_read_b128 v[136:139], v204 offset:28672
	ds_read_b128 v[140:143], v204 offset:30720
	ds_read_b128 v[144:147], v205 offset:40960
	ds_read_b128 v[148:151], v205 offset:43008
	s_waitcnt lgkmcnt(7)
	v_mfma_f32_32x32x16_bf16 v[112:127], v[152:155], v[168:171], v[112:127]
	s_waitcnt lgkmcnt(6)
	v_mfma_f32_32x32x16_bf16 v[96:111], v[152:155], v[172:175], v[96:111]
	v_mfma_f32_32x32x16_bf16 v[80:95], v[156:159], v[168:171], v[80:95]
	v_mfma_f32_32x32x16_bf16 v[64:79], v[156:159], v[172:175], v[64:79]
	v_mfma_f32_32x32x16_bf16 v[48:63], v[160:163], v[168:171], v[48:63]
	v_mfma_f32_32x32x16_bf16 v[32:47], v[160:163], v[172:175], v[32:47]
	v_mfma_f32_32x32x16_bf16 v[16:31], v[164:167], v[168:171], v[16:31]
	v_mfma_f32_32x32x16_bf16 v[0:15], v[164:167], v[172:175], v[0:15]
	s_waitcnt lgkmcnt(1)
	v_mfma_f32_32x32x16_bf16 v[112:127], v[128:131], v[144:147], v[112:127]
	s_waitcnt lgkmcnt(0)
	s_barrier
	v_mfma_f32_32x32x16_bf16 v[96:111], v[128:131], v[148:151], v[96:111]
	v_mov_b32_e32 v128, v189
	v_mov_b32_e32 v129, v189
	s_nop 6
	v_cvt_pk_bf16_f32 v112, v112, s0
	v_and_b32_e32 v130, 64, v129
	v_and_b32_e32 v129, 0xffffff80, v129
	v_and_b32_e32 v131, 31, v128
	v_lshrrev_b32_e32 v128, 3, v128
	v_add_u32_e32 v129, s5, v129
	v_and_or_b32 v128, v128, 4, v129
	v_or3_b32 v130, v131, v130, s4
	v_ashrrev_i32_e32 v131, 31, v130
	v_ashrrev_i32_e32 v129, 31, v128
	v_mfma_f32_32x32x16_bf16 v[80:95], v[132:135], v[144:147], v[80:95]
	v_lshl_add_u64 v[130:131], v[130:131], 1, s[14:15]
	v_cvt_pk_bf16_f32 v114, v114, s0
	v_cvt_pk_bf16_f32 v116, v116, s0
	v_cvt_pk_bf16_f32 v118, v118, s0
	v_cvt_pk_bf16_f32 v96, v96, s0
	v_cvt_pk_bf16_f32 v120, v120, s0
	v_cvt_pk_bf16_f32 v122, v122, s0
	v_mfma_f32_32x32x16_bf16 v[64:79], v[132:135], v[148:151], v[64:79]
	v_lshlrev_b64 v[132:133], 12, v[128:129]
	v_lshl_add_u64 v[132:133], v[130:131], 0, v[132:133]
	v_or_b32_e32 v134, 2, v128
	global_store_short v[132:133], v112, off
	v_or_b32_e32 v112, 1, v128
	v_ashrrev_i32_e32 v135, 31, v134
	v_cvt_pk_bf16_f32 v129, v113, s0
	v_ashrrev_i32_e32 v113, 31, v112
	v_lshlrev_b64 v[134:135], 12, v[134:135]
	v_mfma_f32_32x32x16_bf16 v[48:63], v[136:139], v[144:147], v[48:63]
	v_lshlrev_b64 v[112:113], 12, v[112:113]
	v_lshl_add_u64 v[134:135], v[130:131], 0, v[134:135]
	v_lshl_add_u64 v[112:113], v[130:131], 0, v[112:113]
	global_store_short v[134:135], v114, off
	v_or_b32_e32 v114, 3, v128
	global_store_short v[112:113], v129, off
	v_cvt_pk_bf16_f32 v129, v115, s0
	v_mfma_f32_32x32x16_bf16 v[32:47], v[136:139], v[148:151], v[32:47]
	v_or_b32_e32 v136, 8, v128
	v_ashrrev_i32_e32 v137, 31, v136
	v_ashrrev_i32_e32 v115, 31, v114
	v_lshlrev_b64 v[136:137], 12, v[136:137]
	v_lshlrev_b64 v[114:115], 12, v[114:115]
	v_lshl_add_u64 v[136:137], v[130:131], 0, v[136:137]
	v_or_b32_e32 v138, 10, v128
	v_lshl_add_u64 v[114:115], v[130:131], 0, v[114:115]
	global_store_short v[136:137], v116, off
	v_or_b32_e32 v116, 9, v128
	v_ashrrev_i32_e32 v139, 31, v138
	global_store_short v[114:115], v129, off
	v_cvt_pk_bf16_f32 v129, v117, s0
	v_ashrrev_i32_e32 v117, 31, v116
	v_lshlrev_b64 v[138:139], 12, v[138:139]
	v_mfma_f32_32x32x16_bf16 v[16:31], v[140:143], v[144:147], v[16:31]
	v_lshlrev_b64 v[116:117], 12, v[116:117]
	v_lshl_add_u64 v[138:139], v[130:131], 0, v[138:139]
	v_lshl_add_u64 v[116:117], v[130:131], 0, v[116:117]
	global_store_short v[138:139], v118, off
	v_or_b32_e32 v118, 11, v128
	global_store_short v[116:117], v129, off
	v_cvt_pk_bf16_f32 v129, v119, s0
	v_mfma_f32_32x32x16_bf16 v[0:15], v[140:143], v[148:151], v[0:15]
	v_or_b32_e32 v140, 16, v128
	v_ashrrev_i32_e32 v141, 31, v140
	v_ashrrev_i32_e32 v119, 31, v118
	v_lshlrev_b64 v[140:141], 12, v[140:141]
	global_store_short v[132:133], v96, off offset:64
	v_cvt_pk_bf16_f32 v96, v97, s0
	v_lshlrev_b64 v[118:119], 12, v[118:119]
	v_lshl_add_u64 v[140:141], v[130:131], 0, v[140:141]
	v_or_b32_e32 v142, 18, v128
	global_store_short v[112:113], v96, off offset:64
	v_cvt_pk_bf16_f32 v96, v98, s0
	v_lshl_add_u64 v[118:119], v[130:131], 0, v[118:119]
	global_store_short v[140:141], v120, off
	v_or_b32_e32 v120, 17, v128
	v_ashrrev_i32_e32 v143, 31, v142
	global_store_short v[134:135], v96, off offset:64
	v_cvt_pk_bf16_f32 v96, v99, s0
	global_store_short v[118:119], v129, off
	v_cvt_pk_bf16_f32 v129, v121, s0
	v_ashrrev_i32_e32 v121, 31, v120
	v_lshlrev_b64 v[142:143], 12, v[142:143]
	global_store_short v[114:115], v96, off offset:64
	v_cvt_pk_bf16_f32 v96, v100, s0
	v_lshlrev_b64 v[120:121], 12, v[120:121]
	v_lshl_add_u64 v[142:143], v[130:131], 0, v[142:143]
	v_or_b32_e32 v144, 24, v128
	global_store_short v[136:137], v96, off offset:64
	v_cvt_pk_bf16_f32 v96, v101, s0
	v_lshl_add_u64 v[120:121], v[130:131], 0, v[120:121]
	global_store_short v[142:143], v122, off
	v_or_b32_e32 v122, 19, v128
	v_ashrrev_i32_e32 v145, 31, v144
	global_store_short v[116:117], v96, off offset:64
	v_cvt_pk_bf16_f32 v96, v102, s0
	global_store_short v[120:121], v129, off
	v_cvt_pk_bf16_f32 v129, v123, s0
	v_ashrrev_i32_e32 v123, 31, v122
	v_lshlrev_b64 v[144:145], 12, v[144:145]
	global_store_short v[138:139], v96, off offset:64
	v_cvt_pk_bf16_f32 v96, v103, s0
	v_lshlrev_b64 v[122:123], 12, v[122:123]
	v_cvt_pk_bf16_f32 v124, v124, s0
	v_lshl_add_u64 v[144:145], v[130:131], 0, v[144:145]
	v_or_b32_e32 v146, 26, v128
	global_store_short v[118:119], v96, off offset:64
	v_cvt_pk_bf16_f32 v96, v104, s0
	v_lshl_add_u64 v[122:123], v[130:131], 0, v[122:123]
	global_store_short v[144:145], v124, off
	v_or_b32_e32 v124, 25, v128
	v_ashrrev_i32_e32 v147, 31, v146
	global_store_short v[140:141], v96, off offset:64
	v_cvt_pk_bf16_f32 v96, v105, s0
	global_store_short v[122:123], v129, off
	v_cvt_pk_bf16_f32 v129, v125, s0
	v_ashrrev_i32_e32 v125, 31, v124
	v_lshlrev_b64 v[146:147], 12, v[146:147]
	global_store_short v[120:121], v96, off offset:64
	v_cvt_pk_bf16_f32 v96, v106, s0
	v_lshlrev_b64 v[124:125], 12, v[124:125]
	v_cvt_pk_bf16_f32 v126, v126, s0
	v_lshl_add_u64 v[146:147], v[130:131], 0, v[146:147]
	global_store_short v[142:143], v96, off offset:64
	v_cvt_pk_bf16_f32 v96, v107, s0
	v_lshl_add_u64 v[124:125], v[130:131], 0, v[124:125]
	global_store_short v[146:147], v126, off
	v_or_b32_e32 v126, 27, v128
	global_store_short v[122:123], v96, off offset:64
	v_cvt_pk_bf16_f32 v96, v108, s0
	global_store_short v[124:125], v129, off
	v_cvt_pk_bf16_f32 v129, v127, s0
	v_ashrrev_i32_e32 v127, 31, v126
	global_store_short v[144:145], v96, off offset:64
	v_cvt_pk_bf16_f32 v96, v109, s0
	v_lshlrev_b64 v[126:127], 12, v[126:127]
	global_store_short v[124:125], v96, off offset:64
	v_cvt_pk_bf16_f32 v96, v110, s0
	v_lshl_add_u64 v[126:127], v[130:131], 0, v[126:127]
	global_store_short v[146:147], v96, off offset:64
	v_cvt_pk_bf16_f32 v96, v111, s0
	global_store_short v[126:127], v96, off offset:64
	v_or_b32_e32 v96, 32, v128
	v_ashrrev_i32_e32 v97, 31, v96
	v_lshlrev_b64 v[96:97], 12, v[96:97]
	v_cvt_pk_bf16_f32 v80, v80, s0
	v_lshl_add_u64 v[96:97], v[130:131], 0, v[96:97]
	global_store_short v[96:97], v80, off
	v_or_b32_e32 v80, 33, v128
	v_cvt_pk_bf16_f32 v98, v81, s0
	v_ashrrev_i32_e32 v81, 31, v80
	v_lshlrev_b64 v[80:81], 12, v[80:81]
	v_lshl_add_u64 v[80:81], v[130:131], 0, v[80:81]
	global_store_short v[80:81], v98, off
	v_or_b32_e32 v98, 34, v128
	v_ashrrev_i32_e32 v99, 31, v98
	v_lshlrev_b64 v[98:99], 12, v[98:99]
	v_cvt_pk_bf16_f32 v82, v82, s0
	v_lshl_add_u64 v[98:99], v[130:131], 0, v[98:99]
	global_store_short v[98:99], v82, off
	v_or_b32_e32 v82, 35, v128
	v_cvt_pk_bf16_f32 v100, v83, s0
	v_ashrrev_i32_e32 v83, 31, v82
	v_lshlrev_b64 v[82:83], 12, v[82:83]
	v_lshl_add_u64 v[82:83], v[130:131], 0, v[82:83]
	global_store_short v[82:83], v100, off
	v_or_b32_e32 v100, 40, v128
	v_ashrrev_i32_e32 v101, 31, v100
	v_lshlrev_b64 v[100:101], 12, v[100:101]
	v_cvt_pk_bf16_f32 v84, v84, s0
	v_lshl_add_u64 v[100:101], v[130:131], 0, v[100:101]
	global_store_short v[100:101], v84, off
	v_or_b32_e32 v84, 41, v128
	v_cvt_pk_bf16_f32 v102, v85, s0
	v_ashrrev_i32_e32 v85, 31, v84
	v_lshlrev_b64 v[84:85], 12, v[84:85]
	v_lshl_add_u64 v[84:85], v[130:131], 0, v[84:85]
	global_store_short v[84:85], v102, off
	v_or_b32_e32 v102, 42, v128
	v_ashrrev_i32_e32 v103, 31, v102
	v_lshlrev_b64 v[102:103], 12, v[102:103]
	v_cvt_pk_bf16_f32 v86, v86, s0
	v_lshl_add_u64 v[102:103], v[130:131], 0, v[102:103]
	global_store_short v[102:103], v86, off
	v_or_b32_e32 v86, 43, v128
	v_cvt_pk_bf16_f32 v104, v87, s0
	v_ashrrev_i32_e32 v87, 31, v86
	v_lshlrev_b64 v[86:87], 12, v[86:87]
	v_lshl_add_u64 v[86:87], v[130:131], 0, v[86:87]
	global_store_short v[86:87], v104, off
	v_or_b32_e32 v104, 48, v128
	v_ashrrev_i32_e32 v105, 31, v104
	v_lshlrev_b64 v[104:105], 12, v[104:105]
	v_cvt_pk_bf16_f32 v88, v88, s0
	v_lshl_add_u64 v[104:105], v[130:131], 0, v[104:105]
	global_store_short v[104:105], v88, off
	v_or_b32_e32 v88, 49, v128
	v_cvt_pk_bf16_f32 v106, v89, s0
	v_ashrrev_i32_e32 v89, 31, v88
	v_lshlrev_b64 v[88:89], 12, v[88:89]
	v_lshl_add_u64 v[88:89], v[130:131], 0, v[88:89]
	global_store_short v[88:89], v106, off
	v_or_b32_e32 v106, 50, v128
	v_ashrrev_i32_e32 v107, 31, v106
	v_lshlrev_b64 v[106:107], 12, v[106:107]
	v_cvt_pk_bf16_f32 v90, v90, s0
	v_lshl_add_u64 v[106:107], v[130:131], 0, v[106:107]
	global_store_short v[106:107], v90, off
	v_or_b32_e32 v90, 51, v128
	v_cvt_pk_bf16_f32 v108, v91, s0
	v_ashrrev_i32_e32 v91, 31, v90
	v_lshlrev_b64 v[90:91], 12, v[90:91]
	v_lshl_add_u64 v[90:91], v[130:131], 0, v[90:91]
	global_store_short v[90:91], v108, off
	v_or_b32_e32 v108, 56, v128
	v_cvt_pk_bf16_f32 v64, v64, s0
	v_ashrrev_i32_e32 v109, 31, v108
	global_store_short v[96:97], v64, off offset:64
	v_cvt_pk_bf16_f32 v64, v65, s0
	v_lshlrev_b64 v[108:109], 12, v[108:109]
	global_store_short v[80:81], v64, off offset:64
	v_cvt_pk_bf16_f32 v64, v66, s0
	v_cvt_pk_bf16_f32 v92, v92, s0
	v_lshl_add_u64 v[108:109], v[130:131], 0, v[108:109]
	global_store_short v[98:99], v64, off offset:64
	v_cvt_pk_bf16_f32 v64, v67, s0
	global_store_short v[108:109], v92, off
	v_or_b32_e32 v92, 57, v128
	global_store_short v[82:83], v64, off offset:64
	v_cvt_pk_bf16_f32 v64, v68, s0
	v_cvt_pk_bf16_f32 v110, v93, s0
	v_ashrrev_i32_e32 v93, 31, v92
	global_store_short v[100:101], v64, off offset:64
	v_cvt_pk_bf16_f32 v64, v69, s0
	v_lshlrev_b64 v[92:93], 12, v[92:93]
	global_store_short v[84:85], v64, off offset:64
	v_cvt_pk_bf16_f32 v64, v70, s0
	v_lshl_add_u64 v[92:93], v[130:131], 0, v[92:93]
	global_store_short v[102:103], v64, off offset:64
	v_cvt_pk_bf16_f32 v64, v71, s0
	global_store_short v[92:93], v110, off
	v_or_b32_e32 v110, 58, v128
	global_store_short v[86:87], v64, off offset:64
	v_cvt_pk_bf16_f32 v64, v72, s0
	v_ashrrev_i32_e32 v111, 31, v110
	global_store_short v[104:105], v64, off offset:64
	v_cvt_pk_bf16_f32 v64, v73, s0
	v_lshlrev_b64 v[110:111], 12, v[110:111]
	global_store_short v[88:89], v64, off offset:64
	v_cvt_pk_bf16_f32 v64, v74, s0
	v_cvt_pk_bf16_f32 v94, v94, s0
	v_lshl_add_u64 v[110:111], v[130:131], 0, v[110:111]
	global_store_short v[106:107], v64, off offset:64
	v_cvt_pk_bf16_f32 v64, v75, s0
	global_store_short v[110:111], v94, off
	v_or_b32_e32 v94, 59, v128
	global_store_short v[90:91], v64, off offset:64
	v_cvt_pk_bf16_f32 v64, v76, s0
	v_cvt_pk_bf16_f32 v112, v95, s0
	v_ashrrev_i32_e32 v95, 31, v94
	global_store_short v[108:109], v64, off offset:64
	v_cvt_pk_bf16_f32 v64, v77, s0
	v_lshlrev_b64 v[94:95], 12, v[94:95]
	global_store_short v[92:93], v64, off offset:64
	v_cvt_pk_bf16_f32 v64, v78, s0
	v_lshl_add_u64 v[94:95], v[130:131], 0, v[94:95]
	global_store_short v[110:111], v64, off offset:64
	v_cvt_pk_bf16_f32 v64, v79, s0
	global_store_short v[94:95], v64, off offset:64
	v_or_b32_e32 v64, 64, v128
	v_ashrrev_i32_e32 v65, 31, v64
	v_lshlrev_b64 v[64:65], 12, v[64:65]
	v_cvt_pk_bf16_f32 v48, v48, s0
	v_lshl_add_u64 v[64:65], v[130:131], 0, v[64:65]
	global_store_short v[64:65], v48, off
	v_or_b32_e32 v48, 0x41, v128
	v_cvt_pk_bf16_f32 v66, v49, s0
	v_ashrrev_i32_e32 v49, 31, v48
	v_lshlrev_b64 v[48:49], 12, v[48:49]
	v_lshl_add_u64 v[48:49], v[130:131], 0, v[48:49]
	global_store_short v[48:49], v66, off
	v_or_b32_e32 v66, 0x42, v128
	v_ashrrev_i32_e32 v67, 31, v66
	v_lshlrev_b64 v[66:67], 12, v[66:67]
	v_cvt_pk_bf16_f32 v50, v50, s0
	v_lshl_add_u64 v[66:67], v[130:131], 0, v[66:67]
	global_store_short v[66:67], v50, off
	v_or_b32_e32 v50, 0x43, v128
	v_cvt_pk_bf16_f32 v68, v51, s0
	v_ashrrev_i32_e32 v51, 31, v50
	v_lshlrev_b64 v[50:51], 12, v[50:51]
	v_lshl_add_u64 v[50:51], v[130:131], 0, v[50:51]
	global_store_short v[50:51], v68, off
	v_or_b32_e32 v68, 0x48, v128
	v_ashrrev_i32_e32 v69, 31, v68
	v_lshlrev_b64 v[68:69], 12, v[68:69]
	v_cvt_pk_bf16_f32 v52, v52, s0
	v_lshl_add_u64 v[68:69], v[130:131], 0, v[68:69]
	global_store_short v[68:69], v52, off
	v_or_b32_e32 v52, 0x49, v128
	v_cvt_pk_bf16_f32 v70, v53, s0
	v_ashrrev_i32_e32 v53, 31, v52
	v_lshlrev_b64 v[52:53], 12, v[52:53]
	v_lshl_add_u64 v[52:53], v[130:131], 0, v[52:53]
	global_store_short v[52:53], v70, off
	v_or_b32_e32 v70, 0x4a, v128
	v_ashrrev_i32_e32 v71, 31, v70
	v_lshlrev_b64 v[70:71], 12, v[70:71]
	v_cvt_pk_bf16_f32 v54, v54, s0
	v_lshl_add_u64 v[70:71], v[130:131], 0, v[70:71]
	global_store_short v[70:71], v54, off
	v_or_b32_e32 v54, 0x4b, v128
	v_cvt_pk_bf16_f32 v72, v55, s0
	v_ashrrev_i32_e32 v55, 31, v54
	v_lshlrev_b64 v[54:55], 12, v[54:55]
	v_lshl_add_u64 v[54:55], v[130:131], 0, v[54:55]
	global_store_short v[54:55], v72, off
	v_or_b32_e32 v72, 0x50, v128
	v_ashrrev_i32_e32 v73, 31, v72
	v_lshlrev_b64 v[72:73], 12, v[72:73]
	v_cvt_pk_bf16_f32 v56, v56, s0
	v_lshl_add_u64 v[72:73], v[130:131], 0, v[72:73]
	global_store_short v[72:73], v56, off
	v_or_b32_e32 v56, 0x51, v128
	v_cvt_pk_bf16_f32 v74, v57, s0
	v_ashrrev_i32_e32 v57, 31, v56
	v_lshlrev_b64 v[56:57], 12, v[56:57]
	v_lshl_add_u64 v[56:57], v[130:131], 0, v[56:57]
	global_store_short v[56:57], v74, off
	v_or_b32_e32 v74, 0x52, v128
	v_ashrrev_i32_e32 v75, 31, v74
	v_lshlrev_b64 v[74:75], 12, v[74:75]
	v_cvt_pk_bf16_f32 v58, v58, s0
	v_lshl_add_u64 v[74:75], v[130:131], 0, v[74:75]
	global_store_short v[74:75], v58, off
	v_or_b32_e32 v58, 0x53, v128
	v_cvt_pk_bf16_f32 v76, v59, s0
	v_ashrrev_i32_e32 v59, 31, v58
	v_lshlrev_b64 v[58:59], 12, v[58:59]
	v_lshl_add_u64 v[58:59], v[130:131], 0, v[58:59]
	global_store_short v[58:59], v76, off
	v_or_b32_e32 v76, 0x58, v128
	v_cvt_pk_bf16_f32 v32, v32, s0
	v_ashrrev_i32_e32 v77, 31, v76
	global_store_short v[64:65], v32, off offset:64
	v_cvt_pk_bf16_f32 v32, v33, s0
	v_lshlrev_b64 v[76:77], 12, v[76:77]
	global_store_short v[48:49], v32, off offset:64
	v_cvt_pk_bf16_f32 v32, v34, s0
	v_cvt_pk_bf16_f32 v60, v60, s0
	v_lshl_add_u64 v[76:77], v[130:131], 0, v[76:77]
	global_store_short v[66:67], v32, off offset:64
	v_cvt_pk_bf16_f32 v32, v35, s0
	global_store_short v[76:77], v60, off
	v_or_b32_e32 v60, 0x59, v128
	global_store_short v[50:51], v32, off offset:64
	v_cvt_pk_bf16_f32 v32, v36, s0
	v_cvt_pk_bf16_f32 v78, v61, s0
	v_ashrrev_i32_e32 v61, 31, v60
	global_store_short v[68:69], v32, off offset:64
	v_cvt_pk_bf16_f32 v32, v37, s0
	v_lshlrev_b64 v[60:61], 12, v[60:61]
	global_store_short v[52:53], v32, off offset:64
	v_cvt_pk_bf16_f32 v32, v38, s0
	v_lshl_add_u64 v[60:61], v[130:131], 0, v[60:61]
	global_store_short v[70:71], v32, off offset:64
	v_cvt_pk_bf16_f32 v32, v39, s0
	global_store_short v[60:61], v78, off
	v_or_b32_e32 v78, 0x5a, v128
	global_store_short v[54:55], v32, off offset:64
	v_cvt_pk_bf16_f32 v32, v40, s0
	v_ashrrev_i32_e32 v79, 31, v78
	global_store_short v[72:73], v32, off offset:64
	v_cvt_pk_bf16_f32 v32, v41, s0
	v_lshlrev_b64 v[78:79], 12, v[78:79]
	global_store_short v[56:57], v32, off offset:64
	v_cvt_pk_bf16_f32 v32, v42, s0
	v_cvt_pk_bf16_f32 v62, v62, s0
	v_lshl_add_u64 v[78:79], v[130:131], 0, v[78:79]
	global_store_short v[74:75], v32, off offset:64
	v_cvt_pk_bf16_f32 v32, v43, s0
	global_store_short v[78:79], v62, off
	v_or_b32_e32 v62, 0x5b, v128
	global_store_short v[58:59], v32, off offset:64
	v_cvt_pk_bf16_f32 v32, v44, s0
	v_cvt_pk_bf16_f32 v80, v63, s0
	v_ashrrev_i32_e32 v63, 31, v62
	global_store_short v[76:77], v32, off offset:64
	v_cvt_pk_bf16_f32 v32, v45, s0
	v_lshlrev_b64 v[62:63], 12, v[62:63]
	global_store_short v[60:61], v32, off offset:64
	v_cvt_pk_bf16_f32 v32, v46, s0
	v_lshl_add_u64 v[62:63], v[130:131], 0, v[62:63]
	global_store_short v[78:79], v32, off offset:64
	v_cvt_pk_bf16_f32 v32, v47, s0
	global_store_short v[62:63], v32, off offset:64
	v_or_b32_e32 v32, 0x60, v128
	v_ashrrev_i32_e32 v33, 31, v32
	v_lshlrev_b64 v[32:33], 12, v[32:33]
	v_cvt_pk_bf16_f32 v16, v16, s0
	v_lshl_add_u64 v[32:33], v[130:131], 0, v[32:33]
	global_store_short v[32:33], v16, off
	v_or_b32_e32 v16, 0x61, v128
	v_cvt_pk_bf16_f32 v34, v17, s0
	v_ashrrev_i32_e32 v17, 31, v16
	v_lshlrev_b64 v[16:17], 12, v[16:17]
	v_lshl_add_u64 v[16:17], v[130:131], 0, v[16:17]
	global_store_short v[16:17], v34, off
	v_or_b32_e32 v34, 0x62, v128
	v_ashrrev_i32_e32 v35, 31, v34
	v_lshlrev_b64 v[34:35], 12, v[34:35]
	v_cvt_pk_bf16_f32 v18, v18, s0
	v_lshl_add_u64 v[34:35], v[130:131], 0, v[34:35]
	global_store_short v[34:35], v18, off
	v_or_b32_e32 v18, 0x63, v128
	v_cvt_pk_bf16_f32 v36, v19, s0
	v_ashrrev_i32_e32 v19, 31, v18
	v_lshlrev_b64 v[18:19], 12, v[18:19]
	v_lshl_add_u64 v[18:19], v[130:131], 0, v[18:19]
	global_store_short v[18:19], v36, off
	v_or_b32_e32 v36, 0x68, v128
	v_ashrrev_i32_e32 v37, 31, v36
	v_lshlrev_b64 v[36:37], 12, v[36:37]
	v_cvt_pk_bf16_f32 v20, v20, s0
	v_lshl_add_u64 v[36:37], v[130:131], 0, v[36:37]
	global_store_short v[36:37], v20, off
	v_or_b32_e32 v20, 0x69, v128
	v_cvt_pk_bf16_f32 v38, v21, s0
	v_ashrrev_i32_e32 v21, 31, v20
	v_lshlrev_b64 v[20:21], 12, v[20:21]
	v_lshl_add_u64 v[20:21], v[130:131], 0, v[20:21]
	global_store_short v[20:21], v38, off
	v_or_b32_e32 v38, 0x6a, v128
	v_ashrrev_i32_e32 v39, 31, v38
	v_lshlrev_b64 v[38:39], 12, v[38:39]
	v_cvt_pk_bf16_f32 v22, v22, s0
	v_lshl_add_u64 v[38:39], v[130:131], 0, v[38:39]
	global_store_short v[38:39], v22, off
	v_or_b32_e32 v22, 0x6b, v128
	v_cvt_pk_bf16_f32 v40, v23, s0
	v_ashrrev_i32_e32 v23, 31, v22
	v_lshlrev_b64 v[22:23], 12, v[22:23]
	v_lshl_add_u64 v[22:23], v[130:131], 0, v[22:23]
	global_store_short v[22:23], v40, off
	v_or_b32_e32 v40, 0x70, v128
	v_ashrrev_i32_e32 v41, 31, v40
	v_lshlrev_b64 v[40:41], 12, v[40:41]
	v_cvt_pk_bf16_f32 v24, v24, s0
	v_lshl_add_u64 v[40:41], v[130:131], 0, v[40:41]
	global_store_short v[40:41], v24, off
	v_or_b32_e32 v24, 0x71, v128
	v_cvt_pk_bf16_f32 v42, v25, s0
	v_ashrrev_i32_e32 v25, 31, v24
	v_lshlrev_b64 v[24:25], 12, v[24:25]
	v_lshl_add_u64 v[24:25], v[130:131], 0, v[24:25]
	global_store_short v[24:25], v42, off
	v_or_b32_e32 v42, 0x72, v128
	v_ashrrev_i32_e32 v43, 31, v42
	v_lshlrev_b64 v[42:43], 12, v[42:43]
	v_cvt_pk_bf16_f32 v26, v26, s0
	v_lshl_add_u64 v[42:43], v[130:131], 0, v[42:43]
	global_store_short v[42:43], v26, off
	v_or_b32_e32 v26, 0x73, v128
	v_cvt_pk_bf16_f32 v44, v27, s0
	v_ashrrev_i32_e32 v27, 31, v26
	v_lshlrev_b64 v[26:27], 12, v[26:27]
	v_lshl_add_u64 v[26:27], v[130:131], 0, v[26:27]
	global_store_short v[26:27], v44, off
	v_or_b32_e32 v44, 0x78, v128
	v_cvt_pk_bf16_f32 v0, v0, s0
	v_ashrrev_i32_e32 v45, 31, v44
	global_store_short v[32:33], v0, off offset:64
	v_cvt_pk_bf16_f32 v0, v1, s0
	v_lshlrev_b64 v[44:45], 12, v[44:45]
	global_store_short v[16:17], v0, off offset:64
	v_cvt_pk_bf16_f32 v0, v2, s0
	v_cvt_pk_bf16_f32 v28, v28, s0
	v_lshl_add_u64 v[44:45], v[130:131], 0, v[44:45]
	global_store_short v[34:35], v0, off offset:64
	v_cvt_pk_bf16_f32 v0, v3, s0
	global_store_short v[44:45], v28, off
	v_or_b32_e32 v28, 0x79, v128
	global_store_short v[18:19], v0, off offset:64
	v_cvt_pk_bf16_f32 v0, v4, s0
	v_cvt_pk_bf16_f32 v46, v29, s0
	v_ashrrev_i32_e32 v29, 31, v28
	global_store_short v[36:37], v0, off offset:64
	v_cvt_pk_bf16_f32 v0, v5, s0
	v_lshlrev_b64 v[28:29], 12, v[28:29]
	global_store_short v[20:21], v0, off offset:64
	v_cvt_pk_bf16_f32 v0, v6, s0
	v_lshl_add_u64 v[28:29], v[130:131], 0, v[28:29]
	global_store_short v[38:39], v0, off offset:64
	v_cvt_pk_bf16_f32 v0, v7, s0
	global_store_short v[28:29], v46, off
	v_or_b32_e32 v46, 0x7a, v128
	global_store_short v[22:23], v0, off offset:64
	v_cvt_pk_bf16_f32 v0, v8, s0
	v_ashrrev_i32_e32 v47, 31, v46
	global_store_short v[40:41], v0, off offset:64
	v_cvt_pk_bf16_f32 v0, v9, s0
	v_lshlrev_b64 v[46:47], 12, v[46:47]
	global_store_short v[24:25], v0, off offset:64
	v_cvt_pk_bf16_f32 v0, v10, s0
	v_cvt_pk_bf16_f32 v30, v30, s0
	v_lshl_add_u64 v[46:47], v[130:131], 0, v[46:47]
	global_store_short v[42:43], v0, off offset:64
	v_cvt_pk_bf16_f32 v0, v11, s0
	global_store_short v[46:47], v30, off
	v_or_b32_e32 v30, 0x7b, v128
	global_store_short v[26:27], v0, off offset:64
	v_cvt_pk_bf16_f32 v0, v12, s0
	v_cvt_pk_bf16_f32 v48, v31, s0
	v_ashrrev_i32_e32 v31, 31, v30
	global_store_short v[44:45], v0, off offset:64
	v_cvt_pk_bf16_f32 v0, v13, s0
	v_lshlrev_b64 v[30:31], 12, v[30:31]
	global_store_short v[28:29], v0, off offset:64
	v_cvt_pk_bf16_f32 v0, v14, s0
	v_lshl_add_u64 v[30:31], v[130:131], 0, v[30:31]
	global_store_short v[46:47], v0, off offset:64
	v_cvt_pk_bf16_f32 v0, v15, s0
	s_mov_b64 s[0:1], 0
	global_store_short v[126:127], v129, off
	global_store_short v[94:95], v112, off
	global_store_short v[62:63], v80, off
	global_store_short v[30:31], v48, off
	global_store_short v[30:31], v0, off offset:64

.Lgp9:
	s_min_u32 s7, s6, 60
	s_lshl_b32 s66, s7, 6
	s_add_i32 s8, s66, 0xc0
	s_mov_b32 s9, s67
	s_waitcnt vmcnt(4)
	ds_write_b128 v199, v[152:155] offset:24576
	s_waitcnt vmcnt(3)
	ds_write_b128 v199, v[156:159] offset:28672
	s_waitcnt vmcnt(2)
	ds_write_b128 v199, v[160:163] offset:32768
	s_waitcnt vmcnt(1)
	ds_write_b128 v199, v[164:167] offset:36864
	ds_write_b128 v199, v[168:171] offset:40960
	s_waitcnt vmcnt(0)
	ds_write_b128 v199, v[172:175] offset:45056
	v_lshl_add_u64 v[152:153], v[176:177], 0, s[66:67]
	v_lshl_add_u64 v[156:157], v[180:181], 0, s[8:9]
	v_lshl_add_u64 v[160:161], v[182:183], 0, s[8:9]
	v_lshl_add_u64 v[164:165], v[192:193], 0, s[8:9]
	v_lshl_add_u64 v[168:169], v[178:179], 0, s[66:67]
	v_lshl_add_u64 v[172:173], v[194:195], 0, s[8:9]
	global_load_dwordx4 v[152:155], v[152:153], off offset:192
	s_add_i32 s6, s6, 2
	global_load_dwordx4 v[156:159], v[156:157], off
	s_add_u32 s0, s0, 0x80
	global_load_dwordx4 v[160:163], v[160:161], off
	s_addc_u32 s1, s1, 0
	global_load_dwordx4 v[164:167], v[164:165], off
	s_cmpk_lg_i32 s0, 0xf80
	global_load_dwordx4 v[168:171], v[168:169], off offset:192
	s_nop 0
	global_load_dwordx4 v[172:175], v[172:173], off
	s_waitcnt lgkmcnt(0)
	s_barrier
	s_setprio 1
	s_cbranch_scc1 .LBB0_239
	s_waitcnt vmcnt(5)
	ds_read_b128 v[152:155], v186 offset:24576
	s_waitcnt vmcnt(4)
	ds_read_b128 v[156:159], v186 offset:26624
	s_waitcnt vmcnt(3)
	ds_read_b128 v[160:163], v186 offset:28672
	s_waitcnt vmcnt(2)
	ds_read_b128 v[164:167], v186 offset:30720
	s_waitcnt vmcnt(1)
	ds_read_b128 v[168:171], v203 offset:40960
	s_waitcnt vmcnt(0)
	ds_read_b128 v[172:175], v203 offset:43008
	v_mfma_f32_32x32x16_bf16 v[112:127], v[148:151], v[136:139], v[112:127]
	v_mfma_f32_32x32x16_bf16 v[96:111], v[148:151], v[132:135], v[96:111]
	v_mfma_f32_32x32x16_bf16 v[80:95], v[144:147], v[136:139], v[80:95]
	v_mfma_f32_32x32x16_bf16 v[64:79], v[144:147], v[132:135], v[64:79]
	v_mfma_f32_32x32x16_bf16 v[48:63], v[140:143], v[136:139], v[48:63]
	v_mfma_f32_32x32x16_bf16 v[32:47], v[140:143], v[132:135], v[32:47]
	v_mfma_f32_32x32x16_bf16 v[16:31], v[128:131], v[136:139], v[16:31]
	v_mfma_f32_32x32x16_bf16 v[0:15], v[128:131], v[132:135], v[0:15]
	ds_read_b128 v[128:131], v204 offset:24576
	ds_read_b128 v[132:135], v204 offset:26624
	ds_read_b128 v[136:139], v204 offset:28672
	ds_read_b128 v[140:143], v204 offset:30720
	ds_read_b128 v[144:147], v205 offset:40960
	ds_read_b128 v[148:151], v205 offset:43008
	s_waitcnt lgkmcnt(7)
	v_mfma_f32_32x32x16_bf16 v[112:127], v[152:155], v[168:171], v[112:127]
	s_waitcnt lgkmcnt(6)
	v_mfma_f32_32x32x16_bf16 v[96:111], v[152:155], v[172:175], v[96:111]
	v_mfma_f32_32x32x16_bf16 v[80:95], v[156:159], v[168:171], v[80:95]
	v_mfma_f32_32x32x16_bf16 v[64:79], v[156:159], v[172:175], v[64:79]
	v_mfma_f32_32x32x16_bf16 v[48:63], v[160:163], v[168:171], v[48:63]
	v_mfma_f32_32x32x16_bf16 v[32:47], v[160:163], v[172:175], v[32:47]
	v_mfma_f32_32x32x16_bf16 v[16:31], v[164:167], v[168:171], v[16:31]
	v_mfma_f32_32x32x16_bf16 v[0:15], v[164:167], v[172:175], v[0:15]
	s_waitcnt lgkmcnt(1)
	v_mfma_f32_32x32x16_bf16 v[112:127], v[128:131], v[144:147], v[112:127]
	s_waitcnt lgkmcnt(0)
	s_barrier
	s_mov_b32 s6, 0x9ffe000
	s_mov_b64 s[0:1], 0x8000
	v_mfma_f32_32x32x16_bf16 v[96:111], v[128:131], v[148:151], v[96:111]
	v_and_b32_e32 v152, 63, v189
	v_lshrrev_b32_e32 v153, 6, v189
	v_and_b32_e32 v154, 31, v152
	v_lshrrev_b32_e32 v155, 5, v152
	v_lshrrev_b32_e32 v156, 3, v154
	v_mfma_f32_32x32x16_bf16 v[80:95], v[132:135], v[144:147], v[80:95]
	v_and_b32_e32 v157, 7, v154
	v_lshlrev_b32_e32 v158, 14, v153
	v_lshl_add_u32 v159, v155, 9, v158
	v_lshl_add_u32 v159, v157, 1, v159
	v_lshl_add_u32 v160, v155, 2, v156
	v_mfma_f32_32x32x16_bf16 v[64:79], v[132:135], v[148:151], v[64:79]
	v_xor_b32_e32 v161, 4, v160
	v_lshl_add_u32 v160, v160, 4, v159
	v_lshl_add_u32 v161, v161, 4, v159
	v_lshrrev_b32_e32 v162, 3, v152
	v_and_b32_e32 v163, 7, v152
	v_mfma_f32_32x32x16_bf16 v[48:63], v[136:139], v[144:147], v[48:63]
	v_lshlrev_b32_e32 v164, 2, v155
	v_xor_b32_e32 v164, v163, v164
	v_lshl_add_u32 v165, v162, 7, v158
	v_lshl_add_u32 v166, v164, 4, v165
	v_lshrrev_b32_e32 v167, 1, v153
	v_mfma_f32_32x32x16_bf16 v[32:47], v[136:139], v[148:151], v[32:47]
	v_lshl_add_u32 v167, v167, 7, v162
	v_add_u32_e32 v167, s5, v167
	v_and_b32_e32 v168, 1, v153
	v_lshl_add_u32 v168, v168, 6, s4
	v_lshl_add_u32 v168, v163, 3, v168
	v_mfma_f32_32x32x16_bf16 v[16:31], v[140:143], v[144:147], v[16:31]
	v_lshlrev_b32_e32 v170, 12, v167
	v_lshl_add_u32 v170, v168, 1, v170
	v_add_u32_e32 v170, s6, v170
	v_mov_b32_e32 v171, 0
	v_lshl_add_u64 v[170:171], s[10:11], 0, v[170:171]
	v_mfma_f32_32x32x16_bf16 v[0:15], v[140:143], v[148:151], v[0:15]
	v_mul_f32_e32 v172, 0xbfb8aa3b, v112
	v_mul_f32_e32 v173, 0xbfb8aa3b, v113
	v_mul_f32_e32 v174, 0xbfb8aa3b, v114
	v_mul_f32_e32 v175, 0xbfb8aa3b, v115
	v_exp_f32_e32 v172, v172
	v_exp_f32_e32 v173, v173
	v_exp_f32_e32 v174, v174
	v_exp_f32_e32 v175, v175
	v_add_f32_e32 v172, 1.0, v172
	v_add_f32_e32 v173, 1.0, v173
	v_add_f32_e32 v174, 1.0, v174
	v_add_f32_e32 v175, 1.0, v175
	v_rcp_f32_e32 v172, v172
	v_rcp_f32_e32 v173, v173
	v_rcp_f32_e32 v174, v174
	v_rcp_f32_e32 v175, v175
	v_mul_f32_e32 v112, v112, v172
	v_mul_f32_e32 v113, v113, v173
	v_mul_f32_e32 v114, v114, v174
	v_mul_f32_e32 v115, v115, v175
	v_cvt_pk_bf16_f32 v112, v112, v113
	v_cvt_pk_bf16_f32 v114, v114, v115
	ds_write_b16 v160, v112 offset:0
	ds_write_b16_d16_hi v160, v112 offset:128
	ds_write_b16 v160, v114 offset:256
	ds_write_b16_d16_hi v160, v114 offset:384
	v_mul_f32_e32 v172, 0xbfb8aa3b, v116
	v_mul_f32_e32 v173, 0xbfb8aa3b, v117
	v_mul_f32_e32 v174, 0xbfb8aa3b, v118
	v_mul_f32_e32 v175, 0xbfb8aa3b, v119
	v_exp_f32_e32 v172, v172
	v_exp_f32_e32 v173, v173
	v_exp_f32_e32 v174, v174
	v_exp_f32_e32 v175, v175
	v_add_f32_e32 v172, 1.0, v172
	v_add_f32_e32 v173, 1.0, v173
	v_add_f32_e32 v174, 1.0, v174
	v_add_f32_e32 v175, 1.0, v175
	v_rcp_f32_e32 v172, v172
	v_rcp_f32_e32 v173, v173
	v_rcp_f32_e32 v174, v174
	v_rcp_f32_e32 v175, v175
	v_mul_f32_e32 v116, v116, v172
	v_mul_f32_e32 v117, v117, v173
	v_mul_f32_e32 v118, v118, v174
	v_mul_f32_e32 v119, v119, v175
	v_cvt_pk_bf16_f32 v116, v116, v117
	v_cvt_pk_bf16_f32 v118, v118, v119
	ds_write_b16 v160, v116 offset:1024
	ds_write_b16_d16_hi v160, v116 offset:1152
	ds_write_b16 v160, v118 offset:1280
	ds_write_b16_d16_hi v160, v118 offset:1408
	v_mul_f32_e32 v172, 0xbfb8aa3b, v120
	v_mul_f32_e32 v173, 0xbfb8aa3b, v121
	v_mul_f32_e32 v174, 0xbfb8aa3b, v122
	v_mul_f32_e32 v175, 0xbfb8aa3b, v123
	v_exp_f32_e32 v172, v172
	v_exp_f32_e32 v173, v173
	v_exp_f32_e32 v174, v174
	v_exp_f32_e32 v175, v175
	v_add_f32_e32 v172, 1.0, v172
	v_add_f32_e32 v173, 1.0, v173
	v_add_f32_e32 v174, 1.0, v174
	v_add_f32_e32 v175, 1.0, v175
	v_rcp_f32_e32 v172, v172
	v_rcp_f32_e32 v173, v173
	v_rcp_f32_e32 v174, v174
	v_rcp_f32_e32 v175, v175
	v_mul_f32_e32 v120, v120, v172
	v_mul_f32_e32 v121, v121, v173
	v_mul_f32_e32 v122, v122, v174
	v_mul_f32_e32 v123, v123, v175
	v_cvt_pk_bf16_f32 v120, v120, v121
	v_cvt_pk_bf16_f32 v122, v122, v123
	ds_write_b16 v160, v120 offset:2048
	ds_write_b16_d16_hi v160, v120 offset:2176
	ds_write_b16 v160, v122 offset:2304
	ds_write_b16_d16_hi v160, v122 offset:2432
	v_mul_f32_e32 v172, 0xbfb8aa3b, v124
	v_mul_f32_e32 v173, 0xbfb8aa3b, v125
	v_mul_f32_e32 v174, 0xbfb8aa3b, v126
	v_mul_f32_e32 v175, 0xbfb8aa3b, v127
	v_exp_f32_e32 v172, v172
	v_exp_f32_e32 v173, v173
	v_exp_f32_e32 v174, v174
	v_exp_f32_e32 v175, v175
	v_add_f32_e32 v172, 1.0, v172
	v_add_f32_e32 v173, 1.0, v173
	v_add_f32_e32 v174, 1.0, v174
	v_add_f32_e32 v175, 1.0, v175
	v_rcp_f32_e32 v172, v172
	v_rcp_f32_e32 v173, v173
	v_rcp_f32_e32 v174, v174
	v_rcp_f32_e32 v175, v175
	v_mul_f32_e32 v124, v124, v172
	v_mul_f32_e32 v125, v125, v173
	v_mul_f32_e32 v126, v126, v174
	v_mul_f32_e32 v127, v127, v175
	v_cvt_pk_bf16_f32 v124, v124, v125
	v_cvt_pk_bf16_f32 v126, v126, v127
	ds_write_b16 v160, v124 offset:3072
	ds_write_b16_d16_hi v160, v124 offset:3200
	ds_write_b16 v160, v126 offset:3328
	ds_write_b16_d16_hi v160, v126 offset:3456
	v_mul_f32_e32 v172, 0xbfb8aa3b, v96
	v_mul_f32_e32 v173, 0xbfb8aa3b, v97
	v_mul_f32_e32 v174, 0xbfb8aa3b, v98
	v_mul_f32_e32 v175, 0xbfb8aa3b, v99
	v_exp_f32_e32 v172, v172
	v_exp_f32_e32 v173, v173
	v_exp_f32_e32 v174, v174
	v_exp_f32_e32 v175, v175
	v_add_f32_e32 v172, 1.0, v172
	v_add_f32_e32 v173, 1.0, v173
	v_add_f32_e32 v174, 1.0, v174
	v_add_f32_e32 v175, 1.0, v175
	v_rcp_f32_e32 v172, v172
	v_rcp_f32_e32 v173, v173
	v_rcp_f32_e32 v174, v174
	v_rcp_f32_e32 v175, v175
	v_mul_f32_e32 v96, v96, v172
	v_mul_f32_e32 v97, v97, v173
	v_mul_f32_e32 v98, v98, v174
	v_mul_f32_e32 v99, v99, v175
	v_cvt_pk_bf16_f32 v96, v96, v97
	v_cvt_pk_bf16_f32 v98, v98, v99
	ds_write_b16 v161, v96 offset:0
	ds_write_b16_d16_hi v161, v96 offset:128
	ds_write_b16 v161, v98 offset:256
	ds_write_b16_d16_hi v161, v98 offset:384
	v_mul_f32_e32 v172, 0xbfb8aa3b, v100
	v_mul_f32_e32 v173, 0xbfb8aa3b, v101
	v_mul_f32_e32 v174, 0xbfb8aa3b, v102
	v_mul_f32_e32 v175, 0xbfb8aa3b, v103
	v_exp_f32_e32 v172, v172
	v_exp_f32_e32 v173, v173
	v_exp_f32_e32 v174, v174
	v_exp_f32_e32 v175, v175
	v_add_f32_e32 v172, 1.0, v172
	v_add_f32_e32 v173, 1.0, v173
	v_add_f32_e32 v174, 1.0, v174
	v_add_f32_e32 v175, 1.0, v175
	v_rcp_f32_e32 v172, v172
	v_rcp_f32_e32 v173, v173
	v_rcp_f32_e32 v174, v174
	v_rcp_f32_e32 v175, v175
	v_mul_f32_e32 v100, v100, v172
	v_mul_f32_e32 v101, v101, v173
	v_mul_f32_e32 v102, v102, v174
	v_mul_f32_e32 v103, v103, v175
	v_cvt_pk_bf16_f32 v100, v100, v101
	v_cvt_pk_bf16_f32 v102, v102, v103
	ds_write_b16 v161, v100 offset:1024
	ds_write_b16_d16_hi v161, v100 offset:1152
	ds_write_b16 v161, v102 offset:1280
	ds_write_b16_d16_hi v161, v102 offset:1408
	v_mul_f32_e32 v172, 0xbfb8aa3b, v104
	v_mul_f32_e32 v173, 0xbfb8aa3b, v105
	v_mul_f32_e32 v174, 0xbfb8aa3b, v106
	v_mul_f32_e32 v175, 0xbfb8aa3b, v107
	v_exp_f32_e32 v172, v172
	v_exp_f32_e32 v173, v173
	v_exp_f32_e32 v174, v174
	v_exp_f32_e32 v175, v175
	v_add_f32_e32 v172, 1.0, v172
	v_add_f32_e32 v173, 1.0, v173
	v_add_f32_e32 v174, 1.0, v174
	v_add_f32_e32 v175, 1.0, v175
	v_rcp_f32_e32 v172, v172
	v_rcp_f32_e32 v173, v173
	v_rcp_f32_e32 v174, v174
	v_rcp_f32_e32 v175, v175
	v_mul_f32_e32 v104, v104, v172
	v_mul_f32_e32 v105, v105, v173
	v_mul_f32_e32 v106, v106, v174
	v_mul_f32_e32 v107, v107, v175
	v_cvt_pk_bf16_f32 v104, v104, v105
	v_cvt_pk_bf16_f32 v106, v106, v107
	ds_write_b16 v161, v104 offset:2048
	ds_write_b16_d16_hi v161, v104 offset:2176
	ds_write_b16 v161, v106 offset:2304
	ds_write_b16_d16_hi v161, v106 offset:2432
	v_mul_f32_e32 v172, 0xbfb8aa3b, v108
	v_mul_f32_e32 v173, 0xbfb8aa3b, v109
	v_mul_f32_e32 v174, 0xbfb8aa3b, v110
	v_mul_f32_e32 v175, 0xbfb8aa3b, v111
	v_exp_f32_e32 v172, v172
	v_exp_f32_e32 v173, v173
	v_exp_f32_e32 v174, v174
	v_exp_f32_e32 v175, v175
	v_add_f32_e32 v172, 1.0, v172
	v_add_f32_e32 v173, 1.0, v173
	v_add_f32_e32 v174, 1.0, v174
	v_add_f32_e32 v175, 1.0, v175
	v_rcp_f32_e32 v172, v172
	v_rcp_f32_e32 v173, v173
	v_rcp_f32_e32 v174, v174
	v_rcp_f32_e32 v175, v175
	v_mul_f32_e32 v108, v108, v172
	v_mul_f32_e32 v109, v109, v173
	v_mul_f32_e32 v110, v110, v174
	v_mul_f32_e32 v111, v111, v175
	v_cvt_pk_bf16_f32 v108, v108, v109
	v_cvt_pk_bf16_f32 v110, v110, v111
	ds_write_b16 v161, v108 offset:3072
	ds_write_b16_d16_hi v161, v108 offset:3200
	ds_write_b16 v161, v110 offset:3328
	ds_write_b16_d16_hi v161, v110 offset:3456
	v_mul_f32_e32 v172, 0xbfb8aa3b, v80
	v_mul_f32_e32 v173, 0xbfb8aa3b, v81
	v_mul_f32_e32 v174, 0xbfb8aa3b, v82
	v_mul_f32_e32 v175, 0xbfb8aa3b, v83
	v_exp_f32_e32 v172, v172
	v_exp_f32_e32 v173, v173
	v_exp_f32_e32 v174, v174
	v_exp_f32_e32 v175, v175
	v_add_f32_e32 v172, 1.0, v172
	v_add_f32_e32 v173, 1.0, v173
	v_add_f32_e32 v174, 1.0, v174
	v_add_f32_e32 v175, 1.0, v175
	v_rcp_f32_e32 v172, v172
	v_rcp_f32_e32 v173, v173
	v_rcp_f32_e32 v174, v174
	v_rcp_f32_e32 v175, v175
	v_mul_f32_e32 v80, v80, v172
	v_mul_f32_e32 v81, v81, v173
	v_mul_f32_e32 v82, v82, v174
	v_mul_f32_e32 v83, v83, v175
	v_cvt_pk_bf16_f32 v80, v80, v81
	v_cvt_pk_bf16_f32 v82, v82, v83
	ds_write_b16 v160, v80 offset:4096
	ds_write_b16_d16_hi v160, v80 offset:4224
	ds_write_b16 v160, v82 offset:4352
	ds_write_b16_d16_hi v160, v82 offset:4480
	v_mul_f32_e32 v172, 0xbfb8aa3b, v84
	v_mul_f32_e32 v173, 0xbfb8aa3b, v85
	v_mul_f32_e32 v174, 0xbfb8aa3b, v86
	v_mul_f32_e32 v175, 0xbfb8aa3b, v87
	v_exp_f32_e32 v172, v172
	v_exp_f32_e32 v173, v173
	v_exp_f32_e32 v174, v174
	v_exp_f32_e32 v175, v175
	v_add_f32_e32 v172, 1.0, v172
	v_add_f32_e32 v173, 1.0, v173
	v_add_f32_e32 v174, 1.0, v174
	v_add_f32_e32 v175, 1.0, v175
	v_rcp_f32_e32 v172, v172
	v_rcp_f32_e32 v173, v173
	v_rcp_f32_e32 v174, v174
	v_rcp_f32_e32 v175, v175
	v_mul_f32_e32 v84, v84, v172
	v_mul_f32_e32 v85, v85, v173
	v_mul_f32_e32 v86, v86, v174
	v_mul_f32_e32 v87, v87, v175
	v_cvt_pk_bf16_f32 v84, v84, v85
	v_cvt_pk_bf16_f32 v86, v86, v87
	ds_write_b16 v160, v84 offset:5120
	ds_write_b16_d16_hi v160, v84 offset:5248
	ds_write_b16 v160, v86 offset:5376
	ds_write_b16_d16_hi v160, v86 offset:5504
	v_mul_f32_e32 v172, 0xbfb8aa3b, v88
	v_mul_f32_e32 v173, 0xbfb8aa3b, v89
	v_mul_f32_e32 v174, 0xbfb8aa3b, v90
	v_mul_f32_e32 v175, 0xbfb8aa3b, v91
	v_exp_f32_e32 v172, v172
	v_exp_f32_e32 v173, v173
	v_exp_f32_e32 v174, v174
	v_exp_f32_e32 v175, v175
	v_add_f32_e32 v172, 1.0, v172
	v_add_f32_e32 v173, 1.0, v173
	v_add_f32_e32 v174, 1.0, v174
	v_add_f32_e32 v175, 1.0, v175
	v_rcp_f32_e32 v172, v172
	v_rcp_f32_e32 v173, v173
	v_rcp_f32_e32 v174, v174
	v_rcp_f32_e32 v175, v175
	v_mul_f32_e32 v88, v88, v172
	v_mul_f32_e32 v89, v89, v173
	v_mul_f32_e32 v90, v90, v174
	v_mul_f32_e32 v91, v91, v175
	v_cvt_pk_bf16_f32 v88, v88, v89
	v_cvt_pk_bf16_f32 v90, v90, v91
	ds_write_b16 v160, v88 offset:6144
	ds_write_b16_d16_hi v160, v88 offset:6272
	ds_write_b16 v160, v90 offset:6400
	ds_write_b16_d16_hi v160, v90 offset:6528
	v_mul_f32_e32 v172, 0xbfb8aa3b, v92
	v_mul_f32_e32 v173, 0xbfb8aa3b, v93
	v_mul_f32_e32 v174, 0xbfb8aa3b, v94
	v_mul_f32_e32 v175, 0xbfb8aa3b, v95
	v_exp_f32_e32 v172, v172
	v_exp_f32_e32 v173, v173
	v_exp_f32_e32 v174, v174
	v_exp_f32_e32 v175, v175
	v_add_f32_e32 v172, 1.0, v172
	v_add_f32_e32 v173, 1.0, v173
	v_add_f32_e32 v174, 1.0, v174
	v_add_f32_e32 v175, 1.0, v175
	v_rcp_f32_e32 v172, v172
	v_rcp_f32_e32 v173, v173
	v_rcp_f32_e32 v174, v174
	v_rcp_f32_e32 v175, v175
	v_mul_f32_e32 v92, v92, v172
	v_mul_f32_e32 v93, v93, v173
	v_mul_f32_e32 v94, v94, v174
	v_mul_f32_e32 v95, v95, v175
	v_cvt_pk_bf16_f32 v92, v92, v93
	v_cvt_pk_bf16_f32 v94, v94, v95
	ds_write_b16 v160, v92 offset:7168
	ds_write_b16_d16_hi v160, v92 offset:7296
	ds_write_b16 v160, v94 offset:7424
	ds_write_b16_d16_hi v160, v94 offset:7552
	v_mul_f32_e32 v172, 0xbfb8aa3b, v64
	v_mul_f32_e32 v173, 0xbfb8aa3b, v65
	v_mul_f32_e32 v174, 0xbfb8aa3b, v66
	v_mul_f32_e32 v175, 0xbfb8aa3b, v67
	v_exp_f32_e32 v172, v172
	v_exp_f32_e32 v173, v173
	v_exp_f32_e32 v174, v174
	v_exp_f32_e32 v175, v175
	v_add_f32_e32 v172, 1.0, v172
	v_add_f32_e32 v173, 1.0, v173
	v_add_f32_e32 v174, 1.0, v174
	v_add_f32_e32 v175, 1.0, v175
	v_rcp_f32_e32 v172, v172
	v_rcp_f32_e32 v173, v173
	v_rcp_f32_e32 v174, v174
	v_rcp_f32_e32 v175, v175
	v_mul_f32_e32 v64, v64, v172
	v_mul_f32_e32 v65, v65, v173
	v_mul_f32_e32 v66, v66, v174
	v_mul_f32_e32 v67, v67, v175
	v_cvt_pk_bf16_f32 v64, v64, v65
	v_cvt_pk_bf16_f32 v66, v66, v67
	ds_write_b16 v161, v64 offset:4096
	ds_write_b16_d16_hi v161, v64 offset:4224
	ds_write_b16 v161, v66 offset:4352
	ds_write_b16_d16_hi v161, v66 offset:4480
	v_mul_f32_e32 v172, 0xbfb8aa3b, v68
	v_mul_f32_e32 v173, 0xbfb8aa3b, v69
	v_mul_f32_e32 v174, 0xbfb8aa3b, v70
	v_mul_f32_e32 v175, 0xbfb8aa3b, v71
	v_exp_f32_e32 v172, v172
	v_exp_f32_e32 v173, v173
	v_exp_f32_e32 v174, v174
	v_exp_f32_e32 v175, v175
	v_add_f32_e32 v172, 1.0, v172
	v_add_f32_e32 v173, 1.0, v173
	v_add_f32_e32 v174, 1.0, v174
	v_add_f32_e32 v175, 1.0, v175
	v_rcp_f32_e32 v172, v172
	v_rcp_f32_e32 v173, v173
	v_rcp_f32_e32 v174, v174
	v_rcp_f32_e32 v175, v175
	v_mul_f32_e32 v68, v68, v172
	v_mul_f32_e32 v69, v69, v173
	v_mul_f32_e32 v70, v70, v174
	v_mul_f32_e32 v71, v71, v175
	v_cvt_pk_bf16_f32 v68, v68, v69
	v_cvt_pk_bf16_f32 v70, v70, v71
	ds_write_b16 v161, v68 offset:5120
	ds_write_b16_d16_hi v161, v68 offset:5248
	ds_write_b16 v161, v70 offset:5376
	ds_write_b16_d16_hi v161, v70 offset:5504
	v_mul_f32_e32 v172, 0xbfb8aa3b, v72
	v_mul_f32_e32 v173, 0xbfb8aa3b, v73
	v_mul_f32_e32 v174, 0xbfb8aa3b, v74
	v_mul_f32_e32 v175, 0xbfb8aa3b, v75
	v_exp_f32_e32 v172, v172
	v_exp_f32_e32 v173, v173
	v_exp_f32_e32 v174, v174
	v_exp_f32_e32 v175, v175
	v_add_f32_e32 v172, 1.0, v172
	v_add_f32_e32 v173, 1.0, v173
	v_add_f32_e32 v174, 1.0, v174
	v_add_f32_e32 v175, 1.0, v175
	v_rcp_f32_e32 v172, v172
	v_rcp_f32_e32 v173, v173
	v_rcp_f32_e32 v174, v174
	v_rcp_f32_e32 v175, v175
	v_mul_f32_e32 v72, v72, v172
	v_mul_f32_e32 v73, v73, v173
	v_mul_f32_e32 v74, v74, v174
	v_mul_f32_e32 v75, v75, v175
	v_cvt_pk_bf16_f32 v72, v72, v73
	v_cvt_pk_bf16_f32 v74, v74, v75
	ds_write_b16 v161, v72 offset:6144
	ds_write_b16_d16_hi v161, v72 offset:6272
	ds_write_b16 v161, v74 offset:6400
	ds_write_b16_d16_hi v161, v74 offset:6528
	v_mul_f32_e32 v172, 0xbfb8aa3b, v76
	v_mul_f32_e32 v173, 0xbfb8aa3b, v77
	v_mul_f32_e32 v174, 0xbfb8aa3b, v78
	v_mul_f32_e32 v175, 0xbfb8aa3b, v79
	v_exp_f32_e32 v172, v172
	v_exp_f32_e32 v173, v173
	v_exp_f32_e32 v174, v174
	v_exp_f32_e32 v175, v175
	v_add_f32_e32 v172, 1.0, v172
	v_add_f32_e32 v173, 1.0, v173
	v_add_f32_e32 v174, 1.0, v174
	v_add_f32_e32 v175, 1.0, v175
	v_rcp_f32_e32 v172, v172
	v_rcp_f32_e32 v173, v173
	v_rcp_f32_e32 v174, v174
	v_rcp_f32_e32 v175, v175
	v_mul_f32_e32 v76, v76, v172
	v_mul_f32_e32 v77, v77, v173
	v_mul_f32_e32 v78, v78, v174
	v_mul_f32_e32 v79, v79, v175
	v_cvt_pk_bf16_f32 v76, v76, v77
	v_cvt_pk_bf16_f32 v78, v78, v79
	ds_write_b16 v161, v76 offset:7168
	ds_write_b16_d16_hi v161, v76 offset:7296
	ds_write_b16 v161, v78 offset:7424
	ds_write_b16_d16_hi v161, v78 offset:7552
	v_mul_f32_e32 v172, 0xbfb8aa3b, v48
	v_mul_f32_e32 v173, 0xbfb8aa3b, v49
	v_mul_f32_e32 v174, 0xbfb8aa3b, v50
	v_mul_f32_e32 v175, 0xbfb8aa3b, v51
	v_exp_f32_e32 v172, v172
	v_exp_f32_e32 v173, v173
	v_exp_f32_e32 v174, v174
	v_exp_f32_e32 v175, v175
	v_add_f32_e32 v172, 1.0, v172
	v_add_f32_e32 v173, 1.0, v173
	v_add_f32_e32 v174, 1.0, v174
	v_add_f32_e32 v175, 1.0, v175
	v_rcp_f32_e32 v172, v172
	v_rcp_f32_e32 v173, v173
	v_rcp_f32_e32 v174, v174
	v_rcp_f32_e32 v175, v175
	v_mul_f32_e32 v48, v48, v172
	v_mul_f32_e32 v49, v49, v173
	v_mul_f32_e32 v50, v50, v174
	v_mul_f32_e32 v51, v51, v175
	v_cvt_pk_bf16_f32 v48, v48, v49
	v_cvt_pk_bf16_f32 v50, v50, v51
	ds_write_b16 v160, v48 offset:8192
	ds_write_b16_d16_hi v160, v48 offset:8320
	ds_write_b16 v160, v50 offset:8448
	ds_write_b16_d16_hi v160, v50 offset:8576
	v_mul_f32_e32 v172, 0xbfb8aa3b, v52
	v_mul_f32_e32 v173, 0xbfb8aa3b, v53
	v_mul_f32_e32 v174, 0xbfb8aa3b, v54
	v_mul_f32_e32 v175, 0xbfb8aa3b, v55
	v_exp_f32_e32 v172, v172
	v_exp_f32_e32 v173, v173
	v_exp_f32_e32 v174, v174
	v_exp_f32_e32 v175, v175
	v_add_f32_e32 v172, 1.0, v172
	v_add_f32_e32 v173, 1.0, v173
	v_add_f32_e32 v174, 1.0, v174
	v_add_f32_e32 v175, 1.0, v175
	v_rcp_f32_e32 v172, v172
	v_rcp_f32_e32 v173, v173
	v_rcp_f32_e32 v174, v174
	v_rcp_f32_e32 v175, v175
	v_mul_f32_e32 v52, v52, v172
	v_mul_f32_e32 v53, v53, v173
	v_mul_f32_e32 v54, v54, v174
	v_mul_f32_e32 v55, v55, v175
	v_cvt_pk_bf16_f32 v52, v52, v53
	v_cvt_pk_bf16_f32 v54, v54, v55
	ds_write_b16 v160, v52 offset:9216
	ds_write_b16_d16_hi v160, v52 offset:9344
	ds_write_b16 v160, v54 offset:9472
	ds_write_b16_d16_hi v160, v54 offset:9600
	v_mul_f32_e32 v172, 0xbfb8aa3b, v56
	v_mul_f32_e32 v173, 0xbfb8aa3b, v57
	v_mul_f32_e32 v174, 0xbfb8aa3b, v58
	v_mul_f32_e32 v175, 0xbfb8aa3b, v59
	v_exp_f32_e32 v172, v172
	v_exp_f32_e32 v173, v173
	v_exp_f32_e32 v174, v174
	v_exp_f32_e32 v175, v175
	v_add_f32_e32 v172, 1.0, v172
	v_add_f32_e32 v173, 1.0, v173
	v_add_f32_e32 v174, 1.0, v174
	v_add_f32_e32 v175, 1.0, v175
	v_rcp_f32_e32 v172, v172
	v_rcp_f32_e32 v173, v173
	v_rcp_f32_e32 v174, v174
	v_rcp_f32_e32 v175, v175
	v_mul_f32_e32 v56, v56, v172
	v_mul_f32_e32 v57, v57, v173
	v_mul_f32_e32 v58, v58, v174
	v_mul_f32_e32 v59, v59, v175
	v_cvt_pk_bf16_f32 v56, v56, v57
	v_cvt_pk_bf16_f32 v58, v58, v59
	ds_write_b16 v160, v56 offset:10240
	ds_write_b16_d16_hi v160, v56 offset:10368
	ds_write_b16 v160, v58 offset:10496
	ds_write_b16_d16_hi v160, v58 offset:10624
	v_mul_f32_e32 v172, 0xbfb8aa3b, v60
	v_mul_f32_e32 v173, 0xbfb8aa3b, v61
	v_mul_f32_e32 v174, 0xbfb8aa3b, v62
	v_mul_f32_e32 v175, 0xbfb8aa3b, v63
	v_exp_f32_e32 v172, v172
	v_exp_f32_e32 v173, v173
	v_exp_f32_e32 v174, v174
	v_exp_f32_e32 v175, v175
	v_add_f32_e32 v172, 1.0, v172
	v_add_f32_e32 v173, 1.0, v173
	v_add_f32_e32 v174, 1.0, v174
	v_add_f32_e32 v175, 1.0, v175
	v_rcp_f32_e32 v172, v172
	v_rcp_f32_e32 v173, v173
	v_rcp_f32_e32 v174, v174
	v_rcp_f32_e32 v175, v175
	v_mul_f32_e32 v60, v60, v172
	v_mul_f32_e32 v61, v61, v173
	v_mul_f32_e32 v62, v62, v174
	v_mul_f32_e32 v63, v63, v175
	v_cvt_pk_bf16_f32 v60, v60, v61
	v_cvt_pk_bf16_f32 v62, v62, v63
	ds_write_b16 v160, v60 offset:11264
	ds_write_b16_d16_hi v160, v60 offset:11392
	ds_write_b16 v160, v62 offset:11520
	ds_write_b16_d16_hi v160, v62 offset:11648
	v_mul_f32_e32 v172, 0xbfb8aa3b, v32
	v_mul_f32_e32 v173, 0xbfb8aa3b, v33
	v_mul_f32_e32 v174, 0xbfb8aa3b, v34
	v_mul_f32_e32 v175, 0xbfb8aa3b, v35
	v_exp_f32_e32 v172, v172
	v_exp_f32_e32 v173, v173
	v_exp_f32_e32 v174, v174
	v_exp_f32_e32 v175, v175
	v_add_f32_e32 v172, 1.0, v172
	v_add_f32_e32 v173, 1.0, v173
	v_add_f32_e32 v174, 1.0, v174
	v_add_f32_e32 v175, 1.0, v175
	v_rcp_f32_e32 v172, v172
	v_rcp_f32_e32 v173, v173
	v_rcp_f32_e32 v174, v174
	v_rcp_f32_e32 v175, v175
	v_mul_f32_e32 v32, v32, v172
	v_mul_f32_e32 v33, v33, v173
	v_mul_f32_e32 v34, v34, v174
	v_mul_f32_e32 v35, v35, v175
	v_cvt_pk_bf16_f32 v32, v32, v33
	v_cvt_pk_bf16_f32 v34, v34, v35
	ds_write_b16 v161, v32 offset:8192
	ds_write_b16_d16_hi v161, v32 offset:8320
	ds_write_b16 v161, v34 offset:8448
	ds_write_b16_d16_hi v161, v34 offset:8576
	v_mul_f32_e32 v172, 0xbfb8aa3b, v36
	v_mul_f32_e32 v173, 0xbfb8aa3b, v37
	v_mul_f32_e32 v174, 0xbfb8aa3b, v38
	v_mul_f32_e32 v175, 0xbfb8aa3b, v39
	v_exp_f32_e32 v172, v172
	v_exp_f32_e32 v173, v173
	v_exp_f32_e32 v174, v174
	v_exp_f32_e32 v175, v175
	v_add_f32_e32 v172, 1.0, v172
	v_add_f32_e32 v173, 1.0, v173
	v_add_f32_e32 v174, 1.0, v174
	v_add_f32_e32 v175, 1.0, v175
	v_rcp_f32_e32 v172, v172
	v_rcp_f32_e32 v173, v173
	v_rcp_f32_e32 v174, v174
	v_rcp_f32_e32 v175, v175
	v_mul_f32_e32 v36, v36, v172
	v_mul_f32_e32 v37, v37, v173
	v_mul_f32_e32 v38, v38, v174
	v_mul_f32_e32 v39, v39, v175
	v_cvt_pk_bf16_f32 v36, v36, v37
	v_cvt_pk_bf16_f32 v38, v38, v39
	ds_write_b16 v161, v36 offset:9216
	ds_write_b16_d16_hi v161, v36 offset:9344
	ds_write_b16 v161, v38 offset:9472
	ds_write_b16_d16_hi v161, v38 offset:9600
	v_mul_f32_e32 v172, 0xbfb8aa3b, v40
	v_mul_f32_e32 v173, 0xbfb8aa3b, v41
	v_mul_f32_e32 v174, 0xbfb8aa3b, v42
	v_mul_f32_e32 v175, 0xbfb8aa3b, v43
	v_exp_f32_e32 v172, v172
	v_exp_f32_e32 v173, v173
	v_exp_f32_e32 v174, v174
	v_exp_f32_e32 v175, v175
	v_add_f32_e32 v172, 1.0, v172
	v_add_f32_e32 v173, 1.0, v173
	v_add_f32_e32 v174, 1.0, v174
	v_add_f32_e32 v175, 1.0, v175
	v_rcp_f32_e32 v172, v172
	v_rcp_f32_e32 v173, v173
	v_rcp_f32_e32 v174, v174
	v_rcp_f32_e32 v175, v175
	v_mul_f32_e32 v40, v40, v172
	v_mul_f32_e32 v41, v41, v173
	v_mul_f32_e32 v42, v42, v174
	v_mul_f32_e32 v43, v43, v175
	v_cvt_pk_bf16_f32 v40, v40, v41
	v_cvt_pk_bf16_f32 v42, v42, v43
	ds_write_b16 v161, v40 offset:10240
	ds_write_b16_d16_hi v161, v40 offset:10368
	ds_write_b16 v161, v42 offset:10496
	ds_write_b16_d16_hi v161, v42 offset:10624
	v_mul_f32_e32 v172, 0xbfb8aa3b, v44
	v_mul_f32_e32 v173, 0xbfb8aa3b, v45
	v_mul_f32_e32 v174, 0xbfb8aa3b, v46
	v_mul_f32_e32 v175, 0xbfb8aa3b, v47
	v_exp_f32_e32 v172, v172
	v_exp_f32_e32 v173, v173
	v_exp_f32_e32 v174, v174
	v_exp_f32_e32 v175, v175
	v_add_f32_e32 v172, 1.0, v172
	v_add_f32_e32 v173, 1.0, v173
	v_add_f32_e32 v174, 1.0, v174
	v_add_f32_e32 v175, 1.0, v175
	v_rcp_f32_e32 v172, v172
	v_rcp_f32_e32 v173, v173
	v_rcp_f32_e32 v174, v174
	v_rcp_f32_e32 v175, v175
	v_mul_f32_e32 v44, v44, v172
	v_mul_f32_e32 v45, v45, v173
	v_mul_f32_e32 v46, v46, v174
	v_mul_f32_e32 v47, v47, v175
	v_cvt_pk_bf16_f32 v44, v44, v45
	v_cvt_pk_bf16_f32 v46, v46, v47
	ds_write_b16 v161, v44 offset:11264
	ds_write_b16_d16_hi v161, v44 offset:11392
	ds_write_b16 v161, v46 offset:11520
	ds_write_b16_d16_hi v161, v46 offset:11648
	v_mul_f32_e32 v172, 0xbfb8aa3b, v16
	v_mul_f32_e32 v173, 0xbfb8aa3b, v17
	v_mul_f32_e32 v174, 0xbfb8aa3b, v18
	v_mul_f32_e32 v175, 0xbfb8aa3b, v19
	v_exp_f32_e32 v172, v172
	v_exp_f32_e32 v173, v173
	v_exp_f32_e32 v174, v174
	v_exp_f32_e32 v175, v175
	v_add_f32_e32 v172, 1.0, v172
	v_add_f32_e32 v173, 1.0, v173
	v_add_f32_e32 v174, 1.0, v174
	v_add_f32_e32 v175, 1.0, v175
	v_rcp_f32_e32 v172, v172
	v_rcp_f32_e32 v173, v173
	v_rcp_f32_e32 v174, v174
	v_rcp_f32_e32 v175, v175
	v_mul_f32_e32 v16, v16, v172
	v_mul_f32_e32 v17, v17, v173
	v_mul_f32_e32 v18, v18, v174
	v_mul_f32_e32 v19, v19, v175
	v_cvt_pk_bf16_f32 v16, v16, v17
	v_cvt_pk_bf16_f32 v18, v18, v19
	ds_write_b16 v160, v16 offset:12288
	ds_write_b16_d16_hi v160, v16 offset:12416
	ds_write_b16 v160, v18 offset:12544
	ds_write_b16_d16_hi v160, v18 offset:12672
	v_mul_f32_e32 v172, 0xbfb8aa3b, v20
	v_mul_f32_e32 v173, 0xbfb8aa3b, v21
	v_mul_f32_e32 v174, 0xbfb8aa3b, v22
	v_mul_f32_e32 v175, 0xbfb8aa3b, v23
	v_exp_f32_e32 v172, v172
	v_exp_f32_e32 v173, v173
	v_exp_f32_e32 v174, v174
	v_exp_f32_e32 v175, v175
	v_add_f32_e32 v172, 1.0, v172
	v_add_f32_e32 v173, 1.0, v173
	v_add_f32_e32 v174, 1.0, v174
	v_add_f32_e32 v175, 1.0, v175
	v_rcp_f32_e32 v172, v172
	v_rcp_f32_e32 v173, v173
	v_rcp_f32_e32 v174, v174
	v_rcp_f32_e32 v175, v175
	v_mul_f32_e32 v20, v20, v172
	v_mul_f32_e32 v21, v21, v173
	v_mul_f32_e32 v22, v22, v174
	v_mul_f32_e32 v23, v23, v175
	v_cvt_pk_bf16_f32 v20, v20, v21
	v_cvt_pk_bf16_f32 v22, v22, v23
	ds_write_b16 v160, v20 offset:13312
	ds_write_b16_d16_hi v160, v20 offset:13440
	ds_write_b16 v160, v22 offset:13568
	ds_write_b16_d16_hi v160, v22 offset:13696
	v_mul_f32_e32 v172, 0xbfb8aa3b, v24
	v_mul_f32_e32 v173, 0xbfb8aa3b, v25
	v_mul_f32_e32 v174, 0xbfb8aa3b, v26
	v_mul_f32_e32 v175, 0xbfb8aa3b, v27
	v_exp_f32_e32 v172, v172
	v_exp_f32_e32 v173, v173
	v_exp_f32_e32 v174, v174
	v_exp_f32_e32 v175, v175
	v_add_f32_e32 v172, 1.0, v172
	v_add_f32_e32 v173, 1.0, v173
	v_add_f32_e32 v174, 1.0, v174
	v_add_f32_e32 v175, 1.0, v175
	v_rcp_f32_e32 v172, v172
	v_rcp_f32_e32 v173, v173
	v_rcp_f32_e32 v174, v174
	v_rcp_f32_e32 v175, v175
	v_mul_f32_e32 v24, v24, v172
	v_mul_f32_e32 v25, v25, v173
	v_mul_f32_e32 v26, v26, v174
	v_mul_f32_e32 v27, v27, v175
	v_cvt_pk_bf16_f32 v24, v24, v25
	v_cvt_pk_bf16_f32 v26, v26, v27
	ds_write_b16 v160, v24 offset:14336
	ds_write_b16_d16_hi v160, v24 offset:14464
	ds_write_b16 v160, v26 offset:14592
	ds_write_b16_d16_hi v160, v26 offset:14720
	v_mul_f32_e32 v172, 0xbfb8aa3b, v28
	v_mul_f32_e32 v173, 0xbfb8aa3b, v29
	v_mul_f32_e32 v174, 0xbfb8aa3b, v30
	v_mul_f32_e32 v175, 0xbfb8aa3b, v31
	v_exp_f32_e32 v172, v172
	v_exp_f32_e32 v173, v173
	v_exp_f32_e32 v174, v174
	v_exp_f32_e32 v175, v175
	v_add_f32_e32 v172, 1.0, v172
	v_add_f32_e32 v173, 1.0, v173
	v_add_f32_e32 v174, 1.0, v174
	v_add_f32_e32 v175, 1.0, v175
	v_rcp_f32_e32 v172, v172
	v_rcp_f32_e32 v173, v173
	v_rcp_f32_e32 v174, v174
	v_rcp_f32_e32 v175, v175
	v_mul_f32_e32 v28, v28, v172
	v_mul_f32_e32 v29, v29, v173
	v_mul_f32_e32 v30, v30, v174
	v_mul_f32_e32 v31, v31, v175
	v_cvt_pk_bf16_f32 v28, v28, v29
	v_cvt_pk_bf16_f32 v30, v30, v31
	ds_write_b16 v160, v28 offset:15360
	ds_write_b16_d16_hi v160, v28 offset:15488
	ds_write_b16 v160, v30 offset:15616
	ds_write_b16_d16_hi v160, v30 offset:15744
	v_mul_f32_e32 v172, 0xbfb8aa3b, v0
	v_mul_f32_e32 v173, 0xbfb8aa3b, v1
	v_mul_f32_e32 v174, 0xbfb8aa3b, v2
	v_mul_f32_e32 v175, 0xbfb8aa3b, v3
	v_exp_f32_e32 v172, v172
	v_exp_f32_e32 v173, v173
	v_exp_f32_e32 v174, v174
	v_exp_f32_e32 v175, v175
	v_add_f32_e32 v172, 1.0, v172
	v_add_f32_e32 v173, 1.0, v173
	v_add_f32_e32 v174, 1.0, v174
	v_add_f32_e32 v175, 1.0, v175
	v_rcp_f32_e32 v172, v172
	v_rcp_f32_e32 v173, v173
	v_rcp_f32_e32 v174, v174
	v_rcp_f32_e32 v175, v175
	v_mul_f32_e32 v0, v0, v172
	v_mul_f32_e32 v1, v1, v173
	v_mul_f32_e32 v2, v2, v174
	v_mul_f32_e32 v3, v3, v175
	v_cvt_pk_bf16_f32 v0, v0, v1
	v_cvt_pk_bf16_f32 v2, v2, v3
	ds_write_b16 v161, v0 offset:12288
	ds_write_b16_d16_hi v161, v0 offset:12416
	ds_write_b16 v161, v2 offset:12544
	ds_write_b16_d16_hi v161, v2 offset:12672
	v_mul_f32_e32 v172, 0xbfb8aa3b, v4
	v_mul_f32_e32 v173, 0xbfb8aa3b, v5
	v_mul_f32_e32 v174, 0xbfb8aa3b, v6
	v_mul_f32_e32 v175, 0xbfb8aa3b, v7
	v_exp_f32_e32 v172, v172
	v_exp_f32_e32 v173, v173
	v_exp_f32_e32 v174, v174
	v_exp_f32_e32 v175, v175
	v_add_f32_e32 v172, 1.0, v172
	v_add_f32_e32 v173, 1.0, v173
	v_add_f32_e32 v174, 1.0, v174
	v_add_f32_e32 v175, 1.0, v175
	v_rcp_f32_e32 v172, v172
	v_rcp_f32_e32 v173, v173
	v_rcp_f32_e32 v174, v174
	v_rcp_f32_e32 v175, v175
	v_mul_f32_e32 v4, v4, v172
	v_mul_f32_e32 v5, v5, v173
	v_mul_f32_e32 v6, v6, v174
	v_mul_f32_e32 v7, v7, v175
	v_cvt_pk_bf16_f32 v4, v4, v5
	v_cvt_pk_bf16_f32 v6, v6, v7
	ds_write_b16 v161, v4 offset:13312
	ds_write_b16_d16_hi v161, v4 offset:13440
	ds_write_b16 v161, v6 offset:13568
	ds_write_b16_d16_hi v161, v6 offset:13696
	v_mul_f32_e32 v172, 0xbfb8aa3b, v8
	v_mul_f32_e32 v173, 0xbfb8aa3b, v9
	v_mul_f32_e32 v174, 0xbfb8aa3b, v10
	v_mul_f32_e32 v175, 0xbfb8aa3b, v11
	v_exp_f32_e32 v172, v172
	v_exp_f32_e32 v173, v173
	v_exp_f32_e32 v174, v174
	v_exp_f32_e32 v175, v175
	v_add_f32_e32 v172, 1.0, v172
	v_add_f32_e32 v173, 1.0, v173
	v_add_f32_e32 v174, 1.0, v174
	v_add_f32_e32 v175, 1.0, v175
	v_rcp_f32_e32 v172, v172
	v_rcp_f32_e32 v173, v173
	v_rcp_f32_e32 v174, v174
	v_rcp_f32_e32 v175, v175
	v_mul_f32_e32 v8, v8, v172
	v_mul_f32_e32 v9, v9, v173
	v_mul_f32_e32 v10, v10, v174
	v_mul_f32_e32 v11, v11, v175
	v_cvt_pk_bf16_f32 v8, v8, v9
	v_cvt_pk_bf16_f32 v10, v10, v11
	ds_write_b16 v161, v8 offset:14336
	ds_write_b16_d16_hi v161, v8 offset:14464
	ds_write_b16 v161, v10 offset:14592
	ds_write_b16_d16_hi v161, v10 offset:14720
	v_mul_f32_e32 v172, 0xbfb8aa3b, v12
	v_mul_f32_e32 v173, 0xbfb8aa3b, v13
	v_mul_f32_e32 v174, 0xbfb8aa3b, v14
	v_mul_f32_e32 v175, 0xbfb8aa3b, v15
	v_exp_f32_e32 v172, v172
	v_exp_f32_e32 v173, v173
	v_exp_f32_e32 v174, v174
	v_exp_f32_e32 v175, v175
	v_add_f32_e32 v172, 1.0, v172
	v_add_f32_e32 v173, 1.0, v173
	v_add_f32_e32 v174, 1.0, v174
	v_add_f32_e32 v175, 1.0, v175
	v_rcp_f32_e32 v172, v172
	v_rcp_f32_e32 v173, v173
	v_rcp_f32_e32 v174, v174
	v_rcp_f32_e32 v175, v175
	v_mul_f32_e32 v12, v12, v172
	v_mul_f32_e32 v13, v13, v173
	v_mul_f32_e32 v14, v14, v174
	v_mul_f32_e32 v15, v15, v175
	v_cvt_pk_bf16_f32 v12, v12, v13
	v_cvt_pk_bf16_f32 v14, v14, v15
	ds_write_b16 v161, v12 offset:15360
	ds_write_b16_d16_hi v161, v12 offset:15488
	ds_write_b16 v161, v14 offset:15616
	ds_write_b16_d16_hi v161, v14 offset:15744
	s_waitcnt lgkmcnt(0)
	ds_read_b128 v[128:131], v166 offset:0
	ds_read_b128 v[132:135], v166 offset:1024
	ds_read_b128 v[136:139], v166 offset:2048
	ds_read_b128 v[140:143], v166 offset:3072
	s_waitcnt lgkmcnt(3)
	global_store_dwordx4 v[170:171], v[128:131], off
	v_lshl_add_u64 v[170:171], v[170:171], 0, s[0:1]
	s_waitcnt lgkmcnt(2)
	global_store_dwordx4 v[170:171], v[132:135], off
	v_lshl_add_u64 v[170:171], v[170:171], 0, s[0:1]
	s_waitcnt lgkmcnt(1)
	global_store_dwordx4 v[170:171], v[136:139], off
	v_lshl_add_u64 v[170:171], v[170:171], 0, s[0:1]
	s_waitcnt lgkmcnt(0)
	global_store_dwordx4 v[170:171], v[140:143], off
	v_lshl_add_u64 v[170:171], v[170:171], 0, s[0:1]
	ds_read_b128 v[128:131], v166 offset:4096
	ds_read_b128 v[132:135], v166 offset:5120
	ds_read_b128 v[136:139], v166 offset:6144
	ds_read_b128 v[140:143], v166 offset:7168
	s_waitcnt lgkmcnt(3)
	global_store_dwordx4 v[170:171], v[128:131], off
	v_lshl_add_u64 v[170:171], v[170:171], 0, s[0:1]
	s_waitcnt lgkmcnt(2)
	global_store_dwordx4 v[170:171], v[132:135], off
	v_lshl_add_u64 v[170:171], v[170:171], 0, s[0:1]
	s_waitcnt lgkmcnt(1)
	global_store_dwordx4 v[170:171], v[136:139], off
	v_lshl_add_u64 v[170:171], v[170:171], 0, s[0:1]
	s_waitcnt lgkmcnt(0)
	global_store_dwordx4 v[170:171], v[140:143], off
	v_lshl_add_u64 v[170:171], v[170:171], 0, s[0:1]
	ds_read_b128 v[128:131], v166 offset:8192
	ds_read_b128 v[132:135], v166 offset:9216
	ds_read_b128 v[136:139], v166 offset:10240
	ds_read_b128 v[140:143], v166 offset:11264
	s_waitcnt lgkmcnt(3)
	global_store_dwordx4 v[170:171], v[128:131], off
	v_lshl_add_u64 v[170:171], v[170:171], 0, s[0:1]
	s_waitcnt lgkmcnt(2)
	global_store_dwordx4 v[170:171], v[132:135], off
	v_lshl_add_u64 v[170:171], v[170:171], 0, s[0:1]
	s_waitcnt lgkmcnt(1)
	global_store_dwordx4 v[170:171], v[136:139], off
	v_lshl_add_u64 v[170:171], v[170:171], 0, s[0:1]
	s_waitcnt lgkmcnt(0)
	global_store_dwordx4 v[170:171], v[140:143], off
	v_lshl_add_u64 v[170:171], v[170:171], 0, s[0:1]
	ds_read_b128 v[128:131], v166 offset:12288
	ds_read_b128 v[132:135], v166 offset:13312
	ds_read_b128 v[136:139], v166 offset:14336
	ds_read_b128 v[140:143], v166 offset:15360
	s_waitcnt lgkmcnt(3)
	global_store_dwordx4 v[170:171], v[128:131], off
	v_lshl_add_u64 v[170:171], v[170:171], 0, s[0:1]
	s_waitcnt lgkmcnt(2)
	global_store_dwordx4 v[170:171], v[132:135], off
	v_lshl_add_u64 v[170:171], v[170:171], 0, s[0:1]
	s_waitcnt lgkmcnt(1)
	global_store_dwordx4 v[170:171], v[136:139], off
	v_lshl_add_u64 v[170:171], v[170:171], 0, s[0:1]
	s_waitcnt lgkmcnt(0)
	global_store_dwordx4 v[170:171], v[140:143], off
	v_lshl_add_u64 v[170:171], v[170:171], 0, s[0:1]
	s_mov_b64 s[0:1], 0
	s_barrier

.LBB0_243:
	v_add_u32_e32 v203, v198, v200
	v_add_u32_e32 v186, v201, v200
	ds_read_b128 v[244:247], v203 offset:40960
	ds_read_b128 v[248:251], v203 offset:43008
	ds_read_b128 v[206:209], v186 offset:24576
	ds_read_b128 v[210:213], v186 offset:26624
	ds_read_b128 v[214:217], v186 offset:28672
	ds_read_b128 v[238:241], v186 offset:30720
	v_mfma_f32_32x32x16_bf16 v[112:127], v[136:139], v[148:151], v[112:127]
	v_add_u32_e32 v204, v201, v202
	v_add_u32_e32 v205, v198, v202
	v_mfma_f32_32x32x16_bf16 v[96:111], v[132:135], v[148:151], v[96:111]
	v_mfma_f32_32x32x16_bf16 v[80:95], v[136:139], v[144:147], v[80:95]
	v_mfma_f32_32x32x16_bf16 v[64:79], v[132:135], v[144:147], v[64:79]
	v_mfma_f32_32x32x16_bf16 v[48:63], v[136:139], v[140:143], v[48:63]
	v_mfma_f32_32x32x16_bf16 v[32:47], v[132:135], v[140:143], v[32:47]
	v_mfma_f32_32x32x16_bf16 v[16:31], v[136:139], v[128:131], v[16:31]
	v_mfma_f32_32x32x16_bf16 v[0:15], v[132:135], v[128:131], v[0:15]
	ds_read_b128 v[128:131], v204 offset:24576
	ds_read_b128 v[132:135], v204 offset:26624
	ds_read_b128 v[136:139], v204 offset:28672
	ds_read_b128 v[140:143], v204 offset:30720
	ds_read_b128 v[144:147], v205 offset:40960
	ds_read_b128 v[148:151], v205 offset:43008
	s_waitcnt lgkmcnt(9)
	v_mfma_f32_32x32x16_bf16 v[112:127], v[244:247], v[206:209], v[112:127]
	v_mfma_f32_32x32x16_bf16 v[96:111], v[248:251], v[206:209], v[96:111]
	s_waitcnt lgkmcnt(8)
	v_mfma_f32_32x32x16_bf16 v[80:95], v[244:247], v[210:213], v[80:95]
	v_mfma_f32_32x32x16_bf16 v[64:79], v[248:251], v[210:213], v[64:79]
	s_waitcnt lgkmcnt(7)
	v_mfma_f32_32x32x16_bf16 v[48:63], v[244:247], v[214:217], v[48:63]
	v_mfma_f32_32x32x16_bf16 v[32:47], v[248:251], v[214:217], v[32:47]
	s_waitcnt lgkmcnt(6)
	v_mfma_f32_32x32x16_bf16 v[16:31], v[244:247], v[238:241], v[16:31]
	v_mfma_f32_32x32x16_bf16 v[0:15], v[248:251], v[238:241], v[0:15]
	s_getreg_b32 s39, hwreg(HW_REG_HW_ID, 0, 4)
	s_bitcmp1_b32 s39, 0
	s_cbranch_scc1 .Lgp10
	s_setprio 0
.Lgp10:
	s_waitcnt vmcnt(2)
	ds_write_b128 v199, v[164:167] offset:12288
	v_lshl_add_u64 v[164:165], v[196:197], 0, s[0:1]
	ds_write_b128 v199, v[152:155]
	v_add_co_u32_e32 v152, vcc, s92, v164
	ds_write_b128 v199, v[156:159] offset:4096
	s_nop 0
	v_addc_co_u32_e32 v153, vcc, 0, v165, vcc
	v_add_co_u32_e32 v156, vcc, s93, v164
	ds_write_b128 v199, v[160:163] offset:8192
	s_nop 0
	v_addc_co_u32_e32 v157, vcc, 0, v165, vcc
	v_add_co_u32_e32 v160, vcc, s88, v164
	s_waitcnt vmcnt(0)
	ds_write_b128 v199, v[172:175] offset:20480
	v_addc_co_u32_e32 v161, vcc, 0, v165, vcc
	v_add_co_u32_e32 v164, vcc, s89, v164
	v_lshl_add_u64 v[172:173], v[178:179], 0, s[0:1]
	s_nop 0
	v_addc_co_u32_e32 v165, vcc, 0, v165, vcc
	ds_write_b128 v199, v[168:171] offset:16384
	global_load_dwordx4 v[168:171], v[172:173], off offset:192
	v_add_co_u32_e32 v172, vcc, s78, v172
	global_load_dwordx4 v[152:155], v[152:153], off offset:192
	s_nop 0
	v_addc_co_u32_e32 v173, vcc, 0, v173, vcc
	global_load_dwordx4 v[156:159], v[156:157], off offset:192
	s_nop 0
	global_load_dwordx4 v[160:163], v[160:161], off offset:192
	s_nop 0
	global_load_dwordx4 v[164:167], v[164:165], off offset:192
	s_nop 0
	global_load_dwordx4 v[172:175], v[172:173], off offset:192
	s_waitcnt lgkmcnt(0)
	s_barrier
	s_setprio 1
	ds_read_b128 v[244:247], v203 offset:16384
	ds_read_b128 v[248:251], v203 offset:18432
	ds_read_b128 v[206:209], v186
	ds_read_b128 v[210:213], v186 offset:2048
	ds_read_b128 v[214:217], v186 offset:4096
	ds_read_b128 v[238:241], v186 offset:6144
	v_mfma_f32_32x32x16_bf16 v[112:127], v[144:147], v[128:131], v[112:127]
	v_mfma_f32_32x32x16_bf16 v[96:111], v[148:151], v[128:131], v[96:111]
	v_mfma_f32_32x32x16_bf16 v[80:95], v[144:147], v[132:135], v[80:95]
	v_mfma_f32_32x32x16_bf16 v[64:79], v[148:151], v[132:135], v[64:79]
	v_mfma_f32_32x32x16_bf16 v[48:63], v[144:147], v[136:139], v[48:63]
	v_mfma_f32_32x32x16_bf16 v[32:47], v[148:151], v[136:139], v[32:47]
	v_mfma_f32_32x32x16_bf16 v[16:31], v[144:147], v[140:143], v[16:31]
	v_mfma_f32_32x32x16_bf16 v[0:15], v[148:151], v[140:143], v[0:15]
	ds_read_b128 v[148:151], v204
	ds_read_b128 v[144:147], v204 offset:2048
	ds_read_b128 v[140:143], v204 offset:4096
	ds_read_b128 v[128:131], v204 offset:6144
	ds_read_b128 v[136:139], v205 offset:16384
	ds_read_b128 v[132:135], v205 offset:18432
	s_waitcnt lgkmcnt(9)
	v_mfma_f32_32x32x16_bf16 v[112:127], v[244:247], v[206:209], v[112:127]
	v_mfma_f32_32x32x16_bf16 v[96:111], v[248:251], v[206:209], v[96:111]
	s_waitcnt lgkmcnt(8)
	v_mfma_f32_32x32x16_bf16 v[80:95], v[244:247], v[210:213], v[80:95]
	v_mfma_f32_32x32x16_bf16 v[64:79], v[248:251], v[210:213], v[64:79]
	s_waitcnt lgkmcnt(7)
	v_mfma_f32_32x32x16_bf16 v[48:63], v[244:247], v[214:217], v[48:63]
	v_mfma_f32_32x32x16_bf16 v[32:47], v[248:251], v[214:217], v[32:47]
	s_waitcnt lgkmcnt(6)
	v_mfma_f32_32x32x16_bf16 v[16:31], v[244:247], v[238:241], v[16:31]
	v_mfma_f32_32x32x16_bf16 v[0:15], v[248:251], v[238:241], v[0:15]
	s_getreg_b32 s39, hwreg(HW_REG_HW_ID, 0, 4)
	s_bitcmp1_b32 s39, 0
	s_cbranch_scc1 .Lgp11
	s_setprio 0
.Lgp11:
	s_min_u32 s7, s6, 60
	s_lshl_b32 s66, s7, 6
	s_add_i32 s8, s66, 0xc0
	s_mov_b32 s9, s67
	s_waitcnt vmcnt(4)
	ds_write_b128 v199, v[152:155] offset:24576
	s_waitcnt vmcnt(3)
	ds_write_b128 v199, v[156:159] offset:28672
	s_waitcnt vmcnt(2)
	ds_write_b128 v199, v[160:163] offset:32768
	s_waitcnt vmcnt(1)
	ds_write_b128 v199, v[164:167] offset:36864
	ds_write_b128 v199, v[168:171] offset:40960
	s_waitcnt vmcnt(0)
	ds_write_b128 v199, v[172:175] offset:45056
	v_lshl_add_u64 v[152:153], v[176:177], 0, s[66:67]
	v_lshl_add_u64 v[156:157], v[180:181], 0, s[8:9]
	v_lshl_add_u64 v[160:161], v[182:183], 0, s[8:9]
	v_lshl_add_u64 v[164:165], v[192:193], 0, s[8:9]
	v_lshl_add_u64 v[168:169], v[178:179], 0, s[66:67]
	v_lshl_add_u64 v[172:173], v[194:195], 0, s[8:9]
	global_load_dwordx4 v[152:155], v[152:153], off offset:192
	s_add_i32 s6, s6, 2
	global_load_dwordx4 v[156:159], v[156:157], off
	s_add_u32 s0, s0, 0x80
	global_load_dwordx4 v[160:163], v[160:161], off
	s_addc_u32 s1, s1, 0
	global_load_dwordx4 v[164:167], v[164:165], off
	s_cmpk_lg_i32 s0, 0xf80
	global_load_dwordx4 v[168:171], v[168:169], off offset:192
	s_nop 0
	global_load_dwordx4 v[172:175], v[172:173], off
	s_waitcnt lgkmcnt(0)
	s_barrier
	s_setprio 1
	s_cbranch_scc1 .LBB0_243
	s_waitcnt vmcnt(1)
	ds_read_b128 v[168:171], v203 offset:40960
	s_waitcnt vmcnt(0)
	ds_read_b128 v[172:175], v203 offset:43008
	ds_read_b128 v[152:155], v186 offset:24576
	ds_read_b128 v[156:159], v186 offset:26624
	ds_read_b128 v[160:163], v186 offset:28672
	ds_read_b128 v[164:167], v186 offset:30720
	v_mfma_f32_32x32x16_bf16 v[112:127], v[136:139], v[148:151], v[112:127]
	v_mfma_f32_32x32x16_bf16 v[96:111], v[132:135], v[148:151], v[96:111]
	v_mfma_f32_32x32x16_bf16 v[80:95], v[136:139], v[144:147], v[80:95]
	v_mfma_f32_32x32x16_bf16 v[64:79], v[132:135], v[144:147], v[64:79]
	v_mfma_f32_32x32x16_bf16 v[48:63], v[136:139], v[140:143], v[48:63]
	v_mfma_f32_32x32x16_bf16 v[32:47], v[132:135], v[140:143], v[32:47]
	v_mfma_f32_32x32x16_bf16 v[16:31], v[136:139], v[128:131], v[16:31]
	v_mfma_f32_32x32x16_bf16 v[0:15], v[132:135], v[128:131], v[0:15]
	ds_read_b128 v[128:131], v204 offset:24576
	ds_read_b128 v[132:135], v204 offset:26624
	ds_read_b128 v[136:139], v204 offset:28672
	ds_read_b128 v[140:143], v204 offset:30720
	ds_read_b128 v[144:147], v205 offset:40960
	ds_read_b128 v[176:179], v205 offset:43008
	s_waitcnt lgkmcnt(9)
	v_mfma_f32_32x32x16_bf16 v[112:127], v[168:171], v[152:155], v[112:127]
	v_mfma_f32_32x32x16_bf16 v[96:111], v[172:175], v[152:155], v[96:111]
	s_waitcnt lgkmcnt(8)
	v_mfma_f32_32x32x16_bf16 v[80:95], v[168:171], v[156:159], v[80:95]
	v_mfma_f32_32x32x16_bf16 v[64:79], v[172:175], v[156:159], v[64:79]
	s_waitcnt lgkmcnt(7)
	v_mfma_f32_32x32x16_bf16 v[48:63], v[168:171], v[160:163], v[48:63]
	v_mfma_f32_32x32x16_bf16 v[32:47], v[172:175], v[160:163], v[32:47]
	s_waitcnt lgkmcnt(6)
	v_mfma_f32_32x32x16_bf16 v[16:31], v[168:171], v[164:167], v[16:31]
	v_mfma_f32_32x32x16_bf16 v[0:15], v[172:175], v[164:167], v[0:15]
	v_mov_b32_e32 v149, v189
	v_mov_b32_e32 v148, v189
	s_waitcnt lgkmcnt(0)
	s_barrier
	v_mfma_f32_32x32x16_bf16 v[112:127], v[144:147], v[128:131], v[112:127]
	s_addk_i32 s4, 0xf800
	v_and_b32_e32 v148, 63, v189
	v_lshrrev_b32_e32 v149, 6, v189
	v_and_b32_e32 v150, 31, v148
	v_lshrrev_b32_e32 v151, 5, v148
	v_lshrrev_b32_e32 v162, 3, v150
	v_mfma_f32_32x32x16_bf16 v[96:111], v[176:179], v[128:131], v[96:111]
	v_lshlrev_b32_e32 v163, 14, v149
	v_lshl_add_u32 v164, v162, 9, v163
	v_lshl_add_u32 v164, v151, 6, v164
	v_and_b32_e32 v165, 7, v150
	v_lshl_add_u32 v164, v165, 1, v164
	v_mfma_f32_32x32x16_bf16 v[80:95], v[144:147], v[132:135], v[80:95]
	v_lshl_add_u32 v166, v162, 4, v164
	v_xor_b32_e32 v165, 1, v162
	v_lshl_add_u32 v167, v165, 4, v164
	v_xor_b32_e32 v165, 2, v162
	v_lshl_add_u32 v168, v165, 4, v164
	v_xor_b32_e32 v165, 3, v162
	v_lshl_add_u32 v169, v165, 4, v164
	v_mfma_f32_32x32x16_bf16 v[64:79], v[176:179], v[132:135], v[64:79]
	v_lshl_add_u32 v164, v151, 9, v163
	v_xor_b32_e32 v165, v150, v151
	v_lshl_add_u32 v170, v165, 4, v164
	v_xor_b32_e32 v165, 2, v165
	v_lshl_add_u32 v171, v165, 4, v164
	v_mfma_f32_32x32x16_bf16 v[48:63], v[144:147], v[136:139], v[48:63]
	v_and_b32_e32 v164, 1, v149
	v_lshl_add_u32 v164, v164, 6, s4
	v_lshrrev_b32_e32 v165, 1, v149
	v_lshlrev_b32_e32 v165, 7, v165
	v_add_u32_e32 v165, s5, v165
	v_mfma_f32_32x32x16_bf16 v[32:47], v[176:179], v[136:139], v[32:47]
	v_lshrrev_b32_e32 v165, 6, v165
	v_lshlrev_b32_e32 v165, 16, v165
	v_lshl_or_b32 v165, v148, 4, v165
	v_bfe_u32 v163, v164, 5, 4
	v_lshl_or_b32 v165, v163, 12, v165
	v_mfma_f32_32x32x16_bf16 v[16:31], v[144:147], v[140:143], v[16:31]
	v_lshrrev_b32_e32 v163, 9, v164
	v_lshl_or_b32 v152, v163, 23, v165
	v_mov_b32_e32 v153, 0
	v_lshl_add_u64 v[152:153], s[16:17], 0, v[152:153]
	v_mfma_f32_32x32x16_bf16 v[0:15], v[176:179], v[140:143], v[0:15]
	v_add_co_u32_e32 v154, vcc, 0x1000, v152
	s_nop 1
	v_addc_co_u32_e32 v155, vcc, 0, v153, vcc
	v_add_co_u32_e32 v156, vcc, 0x10000, v152
	s_nop 1
	v_addc_co_u32_e32 v157, vcc, 0, v153, vcc
	v_add_co_u32_e32 v158, vcc, 0x11000, v152
	s_nop 1
	v_addc_co_u32_e32 v159, vcc, 0, v153, vcc
	v_cvt_pk_bf16_f32 v112, v112, v112
	ds_write_b16 v166, v112
	v_cvt_pk_bf16_f32 v113, v113, v113
	ds_write_b16 v167, v113
	v_cvt_pk_bf16_f32 v114, v114, v114
	ds_write_b16 v168, v114
	v_cvt_pk_bf16_f32 v115, v115, v115
	ds_write_b16 v169, v115
	v_cvt_pk_bf16_f32 v116, v116, v116
	ds_write_b16 v166, v116 offset:128
	v_cvt_pk_bf16_f32 v117, v117, v117
	ds_write_b16 v167, v117 offset:128
	v_cvt_pk_bf16_f32 v118, v118, v118
	ds_write_b16 v168, v118 offset:128
	v_cvt_pk_bf16_f32 v119, v119, v119
	ds_write_b16 v169, v119 offset:128
	v_cvt_pk_bf16_f32 v120, v120, v120
	ds_write_b16 v166, v120 offset:256
	v_cvt_pk_bf16_f32 v121, v121, v121
	ds_write_b16 v167, v121 offset:256
	v_cvt_pk_bf16_f32 v122, v122, v122
	ds_write_b16 v168, v122 offset:256
	v_cvt_pk_bf16_f32 v123, v123, v123
	ds_write_b16 v169, v123 offset:256
	v_cvt_pk_bf16_f32 v124, v124, v124
	ds_write_b16 v166, v124 offset:384
	v_cvt_pk_bf16_f32 v125, v125, v125
	ds_write_b16 v167, v125 offset:384
	v_cvt_pk_bf16_f32 v126, v126, v126
	ds_write_b16 v168, v126 offset:384
	v_cvt_pk_bf16_f32 v127, v127, v127
	ds_write_b16 v169, v127 offset:384
	v_cvt_pk_bf16_f32 v96, v96, v96
	ds_write_b16 v166, v96 offset:4096
	v_cvt_pk_bf16_f32 v97, v97, v97
	ds_write_b16 v167, v97 offset:4096
	v_cvt_pk_bf16_f32 v98, v98, v98
	ds_write_b16 v168, v98 offset:4096
	v_cvt_pk_bf16_f32 v99, v99, v99
	ds_write_b16 v169, v99 offset:4096
	v_cvt_pk_bf16_f32 v100, v100, v100
	ds_write_b16 v166, v100 offset:4224
	v_cvt_pk_bf16_f32 v101, v101, v101
	ds_write_b16 v167, v101 offset:4224
	v_cvt_pk_bf16_f32 v102, v102, v102
	ds_write_b16 v168, v102 offset:4224
	v_cvt_pk_bf16_f32 v103, v103, v103
	ds_write_b16 v169, v103 offset:4224
	v_cvt_pk_bf16_f32 v104, v104, v104
	ds_write_b16 v166, v104 offset:4352
	v_cvt_pk_bf16_f32 v105, v105, v105
	ds_write_b16 v167, v105 offset:4352
	v_cvt_pk_bf16_f32 v106, v106, v106
	ds_write_b16 v168, v106 offset:4352
	v_cvt_pk_bf16_f32 v107, v107, v107
	ds_write_b16 v169, v107 offset:4352
	v_cvt_pk_bf16_f32 v108, v108, v108
	ds_write_b16 v166, v108 offset:4480
	v_cvt_pk_bf16_f32 v109, v109, v109
	ds_write_b16 v167, v109 offset:4480
	v_cvt_pk_bf16_f32 v110, v110, v110
	ds_write_b16 v168, v110 offset:4480
	v_cvt_pk_bf16_f32 v111, v111, v111
	ds_write_b16 v169, v111 offset:4480
	v_cvt_pk_bf16_f32 v80, v80, v80
	ds_write_b16 v166, v80 offset:2048
	v_cvt_pk_bf16_f32 v81, v81, v81
	ds_write_b16 v167, v81 offset:2048
	v_cvt_pk_bf16_f32 v82, v82, v82
	ds_write_b16 v168, v82 offset:2048
	v_cvt_pk_bf16_f32 v83, v83, v83
	ds_write_b16 v169, v83 offset:2048
	v_cvt_pk_bf16_f32 v84, v84, v84
	ds_write_b16 v166, v84 offset:2176
	v_cvt_pk_bf16_f32 v85, v85, v85
	ds_write_b16 v167, v85 offset:2176
	v_cvt_pk_bf16_f32 v86, v86, v86
	ds_write_b16 v168, v86 offset:2176
	v_cvt_pk_bf16_f32 v87, v87, v87
	ds_write_b16 v169, v87 offset:2176
	v_cvt_pk_bf16_f32 v88, v88, v88
	ds_write_b16 v166, v88 offset:2304
	v_cvt_pk_bf16_f32 v89, v89, v89
	ds_write_b16 v167, v89 offset:2304
	v_cvt_pk_bf16_f32 v90, v90, v90
	ds_write_b16 v168, v90 offset:2304
	v_cvt_pk_bf16_f32 v91, v91, v91
	ds_write_b16 v169, v91 offset:2304
	v_cvt_pk_bf16_f32 v92, v92, v92
	ds_write_b16 v166, v92 offset:2432
	v_cvt_pk_bf16_f32 v93, v93, v93
	ds_write_b16 v167, v93 offset:2432
	v_cvt_pk_bf16_f32 v94, v94, v94
	ds_write_b16 v168, v94 offset:2432
	v_cvt_pk_bf16_f32 v95, v95, v95
	ds_write_b16 v169, v95 offset:2432
	v_cvt_pk_bf16_f32 v64, v64, v64
	ds_write_b16 v166, v64 offset:6144
	v_cvt_pk_bf16_f32 v65, v65, v65
	ds_write_b16 v167, v65 offset:6144
	v_cvt_pk_bf16_f32 v66, v66, v66
	ds_write_b16 v168, v66 offset:6144
	v_cvt_pk_bf16_f32 v67, v67, v67
	ds_write_b16 v169, v67 offset:6144
	v_cvt_pk_bf16_f32 v68, v68, v68
	ds_write_b16 v166, v68 offset:6272
	v_cvt_pk_bf16_f32 v69, v69, v69
	ds_write_b16 v167, v69 offset:6272
	v_cvt_pk_bf16_f32 v70, v70, v70
	ds_write_b16 v168, v70 offset:6272
	v_cvt_pk_bf16_f32 v71, v71, v71
	ds_write_b16 v169, v71 offset:6272
	v_cvt_pk_bf16_f32 v72, v72, v72
	ds_write_b16 v166, v72 offset:6400
	v_cvt_pk_bf16_f32 v73, v73, v73
	ds_write_b16 v167, v73 offset:6400
	v_cvt_pk_bf16_f32 v74, v74, v74
	ds_write_b16 v168, v74 offset:6400
	v_cvt_pk_bf16_f32 v75, v75, v75
	ds_write_b16 v169, v75 offset:6400
	v_cvt_pk_bf16_f32 v76, v76, v76
	ds_write_b16 v166, v76 offset:6528
	v_cvt_pk_bf16_f32 v77, v77, v77
	ds_write_b16 v167, v77 offset:6528
	v_cvt_pk_bf16_f32 v78, v78, v78
	ds_write_b16 v168, v78 offset:6528
	v_cvt_pk_bf16_f32 v79, v79, v79
	ds_write_b16 v169, v79 offset:6528
	v_cvt_pk_bf16_f32 v48, v48, v48
	ds_write_b16 v166, v48 offset:8192
	v_cvt_pk_bf16_f32 v49, v49, v49
	ds_write_b16 v167, v49 offset:8192
	v_cvt_pk_bf16_f32 v50, v50, v50
	ds_write_b16 v168, v50 offset:8192
	v_cvt_pk_bf16_f32 v51, v51, v51
	ds_write_b16 v169, v51 offset:8192
	v_cvt_pk_bf16_f32 v52, v52, v52
	ds_write_b16 v166, v52 offset:8320
	v_cvt_pk_bf16_f32 v53, v53, v53
	ds_write_b16 v167, v53 offset:8320
	v_cvt_pk_bf16_f32 v54, v54, v54
	ds_write_b16 v168, v54 offset:8320
	v_cvt_pk_bf16_f32 v55, v55, v55
	ds_write_b16 v169, v55 offset:8320
	v_cvt_pk_bf16_f32 v56, v56, v56
	ds_write_b16 v166, v56 offset:8448
	v_cvt_pk_bf16_f32 v57, v57, v57
	ds_write_b16 v167, v57 offset:8448
	v_cvt_pk_bf16_f32 v58, v58, v58
	ds_write_b16 v168, v58 offset:8448
	v_cvt_pk_bf16_f32 v59, v59, v59
	ds_write_b16 v169, v59 offset:8448
	v_cvt_pk_bf16_f32 v60, v60, v60
	ds_write_b16 v166, v60 offset:8576
	v_cvt_pk_bf16_f32 v61, v61, v61
	ds_write_b16 v167, v61 offset:8576
	v_cvt_pk_bf16_f32 v62, v62, v62
	ds_write_b16 v168, v62 offset:8576
	v_cvt_pk_bf16_f32 v63, v63, v63
	ds_write_b16 v169, v63 offset:8576
	v_cvt_pk_bf16_f32 v32, v32, v32
	ds_write_b16 v166, v32 offset:12288
	v_cvt_pk_bf16_f32 v33, v33, v33
	ds_write_b16 v167, v33 offset:12288
	v_cvt_pk_bf16_f32 v34, v34, v34
	ds_write_b16 v168, v34 offset:12288
	v_cvt_pk_bf16_f32 v35, v35, v35
	ds_write_b16 v169, v35 offset:12288
	v_cvt_pk_bf16_f32 v36, v36, v36
	ds_write_b16 v166, v36 offset:12416
	v_cvt_pk_bf16_f32 v37, v37, v37
	ds_write_b16 v167, v37 offset:12416
	v_cvt_pk_bf16_f32 v38, v38, v38
	ds_write_b16 v168, v38 offset:12416
	v_cvt_pk_bf16_f32 v39, v39, v39
	ds_write_b16 v169, v39 offset:12416
	v_cvt_pk_bf16_f32 v40, v40, v40
	ds_write_b16 v166, v40 offset:12544
	v_cvt_pk_bf16_f32 v41, v41, v41
	ds_write_b16 v167, v41 offset:12544
	v_cvt_pk_bf16_f32 v42, v42, v42
	ds_write_b16 v168, v42 offset:12544
	v_cvt_pk_bf16_f32 v43, v43, v43
	ds_write_b16 v169, v43 offset:12544
	v_cvt_pk_bf16_f32 v44, v44, v44
	ds_write_b16 v166, v44 offset:12672
	v_cvt_pk_bf16_f32 v45, v45, v45
	ds_write_b16 v167, v45 offset:12672
	v_cvt_pk_bf16_f32 v46, v46, v46
	ds_write_b16 v168, v46 offset:12672
	v_cvt_pk_bf16_f32 v47, v47, v47
	ds_write_b16 v169, v47 offset:12672
	v_cvt_pk_bf16_f32 v16, v16, v16
	ds_write_b16 v166, v16 offset:10240
	v_cvt_pk_bf16_f32 v17, v17, v17
	ds_write_b16 v167, v17 offset:10240
	v_cvt_pk_bf16_f32 v18, v18, v18
	ds_write_b16 v168, v18 offset:10240
	v_cvt_pk_bf16_f32 v19, v19, v19
	ds_write_b16 v169, v19 offset:10240
	v_cvt_pk_bf16_f32 v20, v20, v20
	ds_write_b16 v166, v20 offset:10368
	v_cvt_pk_bf16_f32 v21, v21, v21
	ds_write_b16 v167, v21 offset:10368
	v_cvt_pk_bf16_f32 v22, v22, v22
	ds_write_b16 v168, v22 offset:10368
	v_cvt_pk_bf16_f32 v23, v23, v23
	ds_write_b16 v169, v23 offset:10368
	v_cvt_pk_bf16_f32 v24, v24, v24
	ds_write_b16 v166, v24 offset:10496
	v_cvt_pk_bf16_f32 v25, v25, v25
	ds_write_b16 v167, v25 offset:10496
	v_cvt_pk_bf16_f32 v26, v26, v26
	ds_write_b16 v168, v26 offset:10496
	v_cvt_pk_bf16_f32 v27, v27, v27
	ds_write_b16 v169, v27 offset:10496
	v_cvt_pk_bf16_f32 v28, v28, v28
	ds_write_b16 v166, v28 offset:10624
	v_cvt_pk_bf16_f32 v29, v29, v29
	ds_write_b16 v167, v29 offset:10624
	v_cvt_pk_bf16_f32 v30, v30, v30
	ds_write_b16 v168, v30 offset:10624
	v_cvt_pk_bf16_f32 v31, v31, v31
	ds_write_b16 v169, v31 offset:10624
	v_cvt_pk_bf16_f32 v0, v0, v0
	ds_write_b16 v166, v0 offset:14336
	v_cvt_pk_bf16_f32 v1, v1, v1
	ds_write_b16 v167, v1 offset:14336
	v_cvt_pk_bf16_f32 v2, v2, v2
	ds_write_b16 v168, v2 offset:14336
	v_cvt_pk_bf16_f32 v3, v3, v3
	ds_write_b16 v169, v3 offset:14336
	v_cvt_pk_bf16_f32 v4, v4, v4
	ds_write_b16 v166, v4 offset:14464
	v_cvt_pk_bf16_f32 v5, v5, v5
	ds_write_b16 v167, v5 offset:14464
	v_cvt_pk_bf16_f32 v6, v6, v6
	ds_write_b16 v168, v6 offset:14464
	v_cvt_pk_bf16_f32 v7, v7, v7
	ds_write_b16 v169, v7 offset:14464
	v_cvt_pk_bf16_f32 v8, v8, v8
	ds_write_b16 v166, v8 offset:14592
	v_cvt_pk_bf16_f32 v9, v9, v9
	ds_write_b16 v167, v9 offset:14592
	v_cvt_pk_bf16_f32 v10, v10, v10
	ds_write_b16 v168, v10 offset:14592
	v_cvt_pk_bf16_f32 v11, v11, v11
	ds_write_b16 v169, v11 offset:14592
	v_cvt_pk_bf16_f32 v12, v12, v12
	ds_write_b16 v166, v12 offset:14720
	v_cvt_pk_bf16_f32 v13, v13, v13
	ds_write_b16 v167, v13 offset:14720
	v_cvt_pk_bf16_f32 v14, v14, v14
	ds_write_b16 v168, v14 offset:14720
	v_cvt_pk_bf16_f32 v15, v15, v15
	ds_write_b16 v169, v15 offset:14720
	s_waitcnt lgkmcnt(0)
	ds_read_b128 v[128:131], v170 offset:0
	ds_read_b128 v[132:135], v171 offset:1024
	ds_read_b128 v[136:139], v170 offset:2048
	ds_read_b128 v[140:143], v171 offset:3072
	s_waitcnt lgkmcnt(3)
	global_store_dwordx4 v[152:153], v[128:131], off
	s_waitcnt lgkmcnt(2)
	global_store_dwordx4 v[152:153], v[132:135], off offset:1024
	s_waitcnt lgkmcnt(1)
	global_store_dwordx4 v[152:153], v[136:139], off offset:2048
	s_waitcnt lgkmcnt(0)
	global_store_dwordx4 v[152:153], v[140:143], off offset:3072
	ds_read_b128 v[128:131], v170 offset:4096
	ds_read_b128 v[132:135], v171 offset:5120
	ds_read_b128 v[136:139], v170 offset:6144
	ds_read_b128 v[140:143], v171 offset:7168
	s_waitcnt lgkmcnt(3)
	global_store_dwordx4 v[154:155], v[128:131], off
	s_waitcnt lgkmcnt(2)
	global_store_dwordx4 v[154:155], v[132:135], off offset:1024
	s_waitcnt lgkmcnt(1)
	global_store_dwordx4 v[154:155], v[136:139], off offset:2048
	s_waitcnt lgkmcnt(0)
	global_store_dwordx4 v[154:155], v[140:143], off offset:3072
	ds_read_b128 v[128:131], v170 offset:8192
	ds_read_b128 v[132:135], v171 offset:9216
	ds_read_b128 v[136:139], v170 offset:10240
	ds_read_b128 v[140:143], v171 offset:11264
	s_waitcnt lgkmcnt(3)
	global_store_dwordx4 v[156:157], v[128:131], off
	s_waitcnt lgkmcnt(2)
	global_store_dwordx4 v[156:157], v[132:135], off offset:1024
	s_waitcnt lgkmcnt(1)
	global_store_dwordx4 v[156:157], v[136:139], off offset:2048
	s_waitcnt lgkmcnt(0)
	global_store_dwordx4 v[156:157], v[140:143], off offset:3072
	ds_read_b128 v[128:131], v170 offset:12288
	ds_read_b128 v[132:135], v171 offset:13312
	ds_read_b128 v[136:139], v170 offset:14336
	ds_read_b128 v[140:143], v171 offset:15360
	s_waitcnt lgkmcnt(3)
	global_store_dwordx4 v[158:159], v[128:131], off
	s_waitcnt lgkmcnt(2)
	global_store_dwordx4 v[158:159], v[132:135], off offset:1024
	s_waitcnt lgkmcnt(1)
	global_store_dwordx4 v[158:159], v[136:139], off offset:2048
	s_waitcnt lgkmcnt(0)
	global_store_dwordx4 v[158:159], v[140:143], off offset:3072
	s_barrier
	s_branch .LBB0_231
